# score pass: 3-stage register ring (33 K-row loads in flight per wave instead of 22), on top of PV-pass de-serialisation
# speedup vs baseline: 1.0018x; 1.0018x over previous
; #define LAS __attribute__((address_space(3)))
; DI float bflo(unsigned w) { return __uint_as_float(w << 16); }
; DI float bfhi(unsigned w) { return __uint_as_float(w & 0xffff0000u); }
; DI float bf2f(bf16_t b) { return __uint_as_float((unsigned)b << 16); }
; #define LDS_WAIT() asm volatile("s_waitcnt lgkmcnt(0)" ::: "memory")
; DI void attn_sample_unit(const Params& p, int u, const bf16_t* Q, const bf16_t* Kb, const bf16_t* Vb, bf16_t* att, LAS float* sl, int lane) {
;     const int h = u & 15, t = (u >> 4) & 3, b = u >> 6;
;     const size_t qrow = (size_t)NP + b * 4 + t;
;     const float* ck = p.in[4]; const float* cv = p.in[5];
;     sl[lane] = bf2f(Q[qrow * 1024 + h * 64 + lane]);
;     LDS_WAIT();
;     float mx = -INFINITY;
; #pragma unroll 1
;     for (int e = 0; e < 9; ++e) { const int pat = e / 3, r = e - 3 * pat; const int dil = 1 << (2 * pat);
;         const int j = lane + 64 * r; const bool valid = j <= 128; const int idx = 2048 + t - dil * (valid ? j : 0);
;         float dot = 0.f;
;         if (idx >= 2048) { const bf16_t* kp = Kb + ((size_t)NP + b * 4 + (idx - 2048)) * 1024 + h * 64;
; #pragma unroll
;             for (int d8 = 0; d8 < 8; ++d8) { const u32x4 kw = *(const u32x4*)(kp + 8 * d8); const f32x4 q0 = *(const LAS f32x4*)(sl + 8 * d8), q1 = *(const LAS f32x4*)(sl + 8 * d8 + 4);
;                 dot += (bflo(kw.x) * q0[0] + bfhi(kw.x) * q0[1]) + (bflo(kw.y) * q0[2] + bfhi(kw.y) * q0[3]) + (bflo(kw.z) * q1[0] + bfhi(kw.z) * q1[1]) + (bflo(kw.w) * q1[2] + bfhi(kw.w) * q1[3]); } }
;         else { const float* kp = ck + (((size_t)b * 2048 + idx) * 16 + h) * 64;
; #pragma unroll
;             for (int d4 = 0; d4 < 16; ++d4) { const f32x4 kv = *(const f32x4*)(kp + 4 * d4); const f32x4 qv = *(const LAS f32x4*)(sl + 4 * d4); dot += (kv[0] * qv[0] + kv[1] * qv[1]) + (kv[2] * qv[2] + kv[3] * qv[3]); } }
;         if (valid) { sl[64 + pat * 192 + j] = dot; mx = fmaxf(mx, dot); } }
.LBB0_1521:
	s_ashr_i32 s86, s80, 6
	s_lshl_b32 s0, s86, 2
	s_add_i32 s0, s0, 0x8000
	s_and_b32 s4, s80, 3
	s_ashr_i32 s1, s0, 31
	s_or_b32 s76, s0, s4
	s_mov_b32 s77, s1
	s_lshl_b64 s[78:79], s[76:77], 10
	s_bfe_u32 s5, s80, 0x40002
	v_writelane_b32 v254, s78, 12
	s_lshl_b32 s2, s5, 6
	s_lshl_b64 s[76:77], s[76:77], 11
	v_writelane_b32 v254, s79, 13
	v_writelane_b32 v254, s2, 10
	s_mov_b32 s90, s82
	v_readlane_b32 s78, v254, 6
	v_readlane_b32 s79, v254, 7
	s_add_u32 s2, s78, s76
	s_addc_u32 s77, s79, s77
	s_lshl_b32 s78, s5, 7
	s_add_u32 s76, s2, s78
	s_addc_u32 s77, s77, 0
	v_lshl_add_u64 v[0:1], v[128:129], 1, s[76:77]
	global_load_ushort v0, v[0:1], off
	s_or_b32 s2, s4, 0x800
	s_add_u32 s88, s96, s78
	s_addc_u32 s89, s97, 0
	s_ashr_i32 s87, s86, 31
	s_lshl_b32 s78, s5, 8
	s_lshl_b64 s[76:77], s[86:87], 23
	v_readlane_b32 s92, v254, 14
	v_readlane_b32 s93, v254, 15
	s_add_u32 s76, s92, s76
	s_addc_u32 s77, s93, s77
	v_readlane_b32 s94, v254, 16
	s_add_u32 s84, s76, s78
	s_addc_u32 s85, s77, 0
	v_mov_b32_e32 v40, 0xff800000
	v_mov_b32_e32 v41, v128
	v_mov_b32_e32 v42, v210
	s_mov_b32 s94, 0
	v_readlane_b32 s95, v254, 17
	s_waitcnt vmcnt(0)
	v_lshlrev_b32_e32 v0, 16, v0
	ds_write_b32 v145, v0
	s_waitcnt lgkmcnt(0)
	v_lshrrev_b32_e32 v41, 4, v128
	v_and_b32_e32 v42, 15, v128
	v_lshlrev_b32_e32 v43, 4, v42
	v_add_u32_e32 v51, s3, v43
	ds_read_b128 v[44:47], v51
	v_lshlrev_b32_e32 v48, 2, v41
	v_add_u32_e32 v48, s3, v48
	v_add_u32_e32 v48, 0x100, v48
	s_mov_b32 s100, 0x10001
	s_mov_b32 s101, 0x10001
	s_sub_i32 s1, 3, s4
	s_lshl_b32 s1, s1, 4
	s_lshr_b64 s[100:101], s[100:101], s1
	s_mov_b32 s98, 0x10001
	s_mov_b32 s99, 0x10001
	s_xor_b64 s[98:99], s[98:99], s[100:101]
	s_lshl_b32 s1, s0, 11
	s_add_u32 s94, s88, s1
	s_addc_u32 s95, s89, 0
	v_lshlrev_b32_e32 v102, 11, v41
	v_lshl_add_u32 v102, v42, 3, v102
	global_load_dwordx2 v[100:101], v102, s[94:95]
	s_waitcnt lgkmcnt(0)
	v_lshlrev_b32_e32 v49, 0, v41
	v_sub_u32_e32 v49, s2, v49
	v_min_i32_e32 v50, 0x7ff, v49
	v_lshl_add_u32 v49, v49, 12, v43
	v_lshl_add_u32 v50, v50, 12, v43
	s_mov_b64 s[76:77], s[84:85]
	global_load_dwordx4 v[0:3], v50, s[76:77]
	s_sub_u32 s76, s76, 0x4000
	s_subb_u32 s77, s77, 0
	global_load_dwordx4 v[4:7], v49, s[76:77]
	s_sub_u32 s76, s76, 0x4000
	s_subb_u32 s77, s77, 0
	global_load_dwordx4 v[8:11], v49, s[76:77]
	s_sub_u32 s76, s76, 0x4000
	s_subb_u32 s77, s77, 0
	global_load_dwordx4 v[12:15], v49, s[76:77]
	s_sub_u32 s76, s76, 0x4000
	s_subb_u32 s77, s77, 0
	global_load_dwordx4 v[16:19], v49, s[76:77]
	s_sub_u32 s76, s76, 0x4000
	s_subb_u32 s77, s77, 0
	global_load_dwordx4 v[20:23], v49, s[76:77]
	s_sub_u32 s76, s76, 0x4000
	s_subb_u32 s77, s77, 0
	global_load_dwordx4 v[24:27], v49, s[76:77]
	s_sub_u32 s76, s76, 0x4000
	s_subb_u32 s77, s77, 0
	global_load_dwordx4 v[28:31], v49, s[76:77]
	s_sub_u32 s76, s76, 0x4000
	s_subb_u32 s77, s77, 0
	global_load_dwordx4 v[32:35], v49, s[76:77]
	s_sub_u32 s76, s76, 0x4000
	s_subb_u32 s77, s77, 0
	global_load_dwordx4 v[36:39], v49, s[76:77]
	s_sub_u32 s76, s76, 0x4000
	s_subb_u32 s77, s77, 0
	global_load_dwordx4 v[52:55], v49, s[76:77]
	s_sub_u32 s76, s76, 0x4000
	s_subb_u32 s77, s77, 0
	global_load_dwordx4 v[56:59], v49, s[76:77]
	s_sub_u32 s76, s76, 0x4000
	s_subb_u32 s77, s77, 0
	global_load_dwordx4 v[60:63], v49, s[76:77]
	s_sub_u32 s76, s76, 0x4000
	s_subb_u32 s77, s77, 0
	global_load_dwordx4 v[64:67], v49, s[76:77]
	s_sub_u32 s76, s76, 0x4000
	s_subb_u32 s77, s77, 0
	global_load_dwordx4 v[68:71], v49, s[76:77]
	s_sub_u32 s76, s76, 0x4000
	s_subb_u32 s77, s77, 0
	global_load_dwordx4 v[72:75], v49, s[76:77]
	s_sub_u32 s76, s76, 0x4000
	s_subb_u32 s77, s77, 0
	global_load_dwordx4 v[76:79], v49, s[76:77]
	s_sub_u32 s76, s76, 0x4000
	s_subb_u32 s77, s77, 0
	global_load_dwordx4 v[80:83], v49, s[76:77]
	s_sub_u32 s76, s76, 0x4000
	s_subb_u32 s77, s77, 0
	global_load_dwordx4 v[84:87], v49, s[76:77]
	s_sub_u32 s76, s76, 0x4000
	s_subb_u32 s77, s77, 0
	global_load_dwordx4 v[88:91], v49, s[76:77]
	s_sub_u32 s76, s76, 0x4000
	s_subb_u32 s77, s77, 0
	global_load_dwordx4 v[92:95], v49, s[76:77]
	s_sub_u32 s76, s76, 0x4000
	s_subb_u32 s77, s77, 0
	global_load_dwordx4 v[96:99], v49, s[76:77]
	s_sub_u32 s76, s76, 0x4000
	s_subb_u32 s77, s77, 0
	global_load_dwordx4 v[110:113], v49, s[76:77]
	s_sub_u32 s76, s76, 0x4000
	s_subb_u32 s77, s77, 0
	global_load_dwordx4 v[114:117], v49, s[76:77]
	s_sub_u32 s76, s76, 0x4000
	s_subb_u32 s77, s77, 0
	global_load_dwordx4 v[118:121], v49, s[76:77]
	s_sub_u32 s76, s76, 0x4000
	s_subb_u32 s77, s77, 0
	global_load_dwordx4 v[122:125], v49, s[76:77]
	s_sub_u32 s76, s76, 0x4000
	s_subb_u32 s77, s77, 0
	global_load_dwordx4 v[214:217], v49, s[76:77]
	s_sub_u32 s76, s76, 0x4000
	s_subb_u32 s77, s77, 0
	global_load_dwordx4 v[218:221], v49, s[76:77]
	s_sub_u32 s76, s76, 0x4000
	s_subb_u32 s77, s77, 0
	global_load_dwordx4 v[222:225], v49, s[76:77]
	s_sub_u32 s76, s76, 0x4000
	s_subb_u32 s77, s77, 0
	global_load_dwordx4 v[226:229], v49, s[76:77]
	s_sub_u32 s76, s76, 0x4000
	s_subb_u32 s77, s77, 0
	global_load_dwordx4 v[230:233], v49, s[76:77]
	s_sub_u32 s76, s76, 0x4000
	s_subb_u32 s77, s77, 0
	global_load_dwordx4 v[234:237], v49, s[76:77]
	s_sub_u32 s76, s76, 0x4000
	s_subb_u32 s77, s77, 0
	s_mov_b64 exec, 0xffff
	global_load_dwordx4 v[238:241], v49, s[76:77]
	s_mov_b64 exec, -1
	s_waitcnt vmcnt(22)
; #define LAS __attribute__((address_space(3)))
; DI float bflo(unsigned w) { return __uint_as_float(w << 16); }
; DI float bfhi(unsigned w) { return __uint_as_float(w & 0xffff0000u); }
; DI void attn_sample_unit(const Params& p, int u, const bf16_t* Q, const bf16_t* Kb, const bf16_t* Vb, bf16_t* att, LAS float* sl, int lane) {
;     ...
;     for (int e = 0; e < 9; ++e) { const int pat = e / 3, r = e - 3 * pat; const int dil = 1 << (2 * pat);
;         const int j = lane + 64 * r; const bool valid = j <= 128; const int idx = 2048 + t - dil * (valid ? j : 0);
;         float dot = 0.f;
;         if (idx >= 2048) { const bf16_t* kp = Kb + ((size_t)NP + b * 4 + (idx - 2048)) * 1024 + h * 64;
; #pragma unroll
;             for (int d8 = 0; d8 < 8; ++d8) { const u32x4 kw = *(const u32x4*)(kp + 8 * d8); const f32x4 q0 = *(const LAS f32x4*)(sl + 8 * d8), q1 = *(const LAS f32x4*)(sl + 8 * d8 + 4);
;                 dot += (bflo(kw.x) * q0[0] + bfhi(kw.x) * q0[1]) + (bflo(kw.y) * q0[2] + bfhi(kw.y) * q0[3]) + (bflo(kw.z) * q1[0] + bfhi(kw.z) * q1[1]) + (bflo(kw.w) * q1[2] + bfhi(kw.w) * q1[3]); } }
;         else { const float* kp = ck + (((size_t)b * 2048 + idx) * 16 + h) * 64;
; #pragma unroll
;             for (int d4 = 0; d4 < 16; ++d4) { const f32x4 kv = *(const f32x4*)(kp + 4 * d4); const f32x4 qv = *(const LAS f32x4*)(sl + 4 * d4); dot += (kv[0] * qv[0] + kv[1] * qv[1]) + (kv[2] * qv[2] + kv[3] * qv[3]); } }
;         if (valid) { sl[64 + pat * 192 + j] = dot; mx = fmaxf(mx, dot); } }
	v_lshlrev_b32_e32 v104, 16, v100
	v_and_b32_e32 v105, 0xffff0000, v100
	v_lshlrev_b32_e32 v106, 16, v101
	v_and_b32_e32 v107, 0xffff0000, v101
	v_mul_f32_e32 v104, v104, v44
	v_fmac_f32_e32 v104, v105, v45
	v_fmac_f32_e32 v104, v106, v46
	v_fmac_f32_e32 v104, v107, v47
	s_nop 1
	v_add_f32_dpp v104, v104, v104 quad_perm:[1,0,3,2] row_mask:0xf bank_mask:0xf
	s_nop 1
	v_add_f32_dpp v104, v104, v104 quad_perm:[2,3,0,1] row_mask:0xf bank_mask:0xf
	s_nop 1
	v_add_f32_dpp v104, v104, v104 row_half_mirror row_mask:0xf bank_mask:0xf
	s_nop 1
	v_add_f32_dpp v104, v104, v104 row_mirror row_mask:0xf bank_mask:0xf
	s_lshl_b32 s1, s4, 2
	s_add_i32 s1, s1, s3
	s_addk_i32 s1, 0x100
	v_lshlrev_b32_e32 v108, 2, v41
	v_sub_u32_e32 v108, s1, v108
	v_mov_b32_e32 v109, s3
	s_mov_b64 exec, s[100:101]
	ds_write_b32 v108, v104
	v_max_f32_e32 v40, v40, v104
	s_lshl_b32 s1, s4, 4
	s_lshl_b64 s[82:83], 1, s1
	s_mov_b64 exec, s[82:83]
	ds_write_b32 v109, v104 offset:1024
	ds_write_b32 v109, v104 offset:1792
	s_mov_b64 exec, -1
	s_nop 4
	v_mul_f32_e32 v0, v0, v44
	v_mul_f32_e32 v4, v4, v44
	v_mul_f32_e32 v8, v8, v44
	v_mul_f32_e32 v12, v12, v44
	v_mul_f32_e32 v16, v16, v44
	v_mul_f32_e32 v20, v20, v44
	v_mul_f32_e32 v24, v24, v44
	v_mul_f32_e32 v28, v28, v44
	v_mul_f32_e32 v32, v32, v44
	v_mul_f32_e32 v36, v36, v44
	v_mul_f32_e32 v52, v52, v44
	v_fmac_f32_e32 v0, v1, v45
	v_fmac_f32_e32 v4, v5, v45
	v_fmac_f32_e32 v8, v9, v45
	v_fmac_f32_e32 v12, v13, v45
	v_fmac_f32_e32 v16, v17, v45
	v_fmac_f32_e32 v20, v21, v45
	v_fmac_f32_e32 v24, v25, v45
	v_fmac_f32_e32 v28, v29, v45
	v_fmac_f32_e32 v32, v33, v45
	v_fmac_f32_e32 v36, v37, v45
	v_fmac_f32_e32 v52, v53, v45
	v_fmac_f32_e32 v0, v2, v46
	v_fmac_f32_e32 v4, v6, v46
	v_fmac_f32_e32 v8, v10, v46
	v_fmac_f32_e32 v12, v14, v46
	v_fmac_f32_e32 v16, v18, v46
	v_fmac_f32_e32 v20, v22, v46
	v_fmac_f32_e32 v24, v26, v46
	v_fmac_f32_e32 v28, v30, v46
	v_fmac_f32_e32 v32, v34, v46
	v_fmac_f32_e32 v36, v38, v46
	v_fmac_f32_e32 v52, v54, v46
	v_fmac_f32_e32 v0, v3, v47
	v_fmac_f32_e32 v4, v7, v47
	v_fmac_f32_e32 v8, v11, v47
	v_fmac_f32_e32 v12, v15, v47
	v_fmac_f32_e32 v16, v19, v47
	v_fmac_f32_e32 v20, v23, v47
	v_fmac_f32_e32 v24, v27, v47
	v_fmac_f32_e32 v28, v31, v47
	v_fmac_f32_e32 v32, v35, v47
	v_fmac_f32_e32 v36, v39, v47
	v_fmac_f32_e32 v52, v55, v47
	s_nop 1
	v_add_f32_dpp v0, v0, v0 quad_perm:[1,0,3,2] row_mask:0xf bank_mask:0xf
	v_add_f32_dpp v4, v4, v4 quad_perm:[1,0,3,2] row_mask:0xf bank_mask:0xf
	v_add_f32_dpp v8, v8, v8 quad_perm:[1,0,3,2] row_mask:0xf bank_mask:0xf
	v_add_f32_dpp v12, v12, v12 quad_perm:[1,0,3,2] row_mask:0xf bank_mask:0xf
	v_add_f32_dpp v16, v16, v16 quad_perm:[1,0,3,2] row_mask:0xf bank_mask:0xf
	v_add_f32_dpp v20, v20, v20 quad_perm:[1,0,3,2] row_mask:0xf bank_mask:0xf
	v_add_f32_dpp v24, v24, v24 quad_perm:[1,0,3,2] row_mask:0xf bank_mask:0xf
	v_add_f32_dpp v28, v28, v28 quad_perm:[1,0,3,2] row_mask:0xf bank_mask:0xf
	v_add_f32_dpp v32, v32, v32 quad_perm:[1,0,3,2] row_mask:0xf bank_mask:0xf
	v_add_f32_dpp v36, v36, v36 quad_perm:[1,0,3,2] row_mask:0xf bank_mask:0xf
	v_add_f32_dpp v52, v52, v52 quad_perm:[1,0,3,2] row_mask:0xf bank_mask:0xf
	s_nop 1
	v_add_f32_dpp v0, v0, v0 quad_perm:[2,3,0,1] row_mask:0xf bank_mask:0xf
	v_add_f32_dpp v4, v4, v4 quad_perm:[2,3,0,1] row_mask:0xf bank_mask:0xf
	v_add_f32_dpp v8, v8, v8 quad_perm:[2,3,0,1] row_mask:0xf bank_mask:0xf
	v_add_f32_dpp v12, v12, v12 quad_perm:[2,3,0,1] row_mask:0xf bank_mask:0xf
	v_add_f32_dpp v16, v16, v16 quad_perm:[2,3,0,1] row_mask:0xf bank_mask:0xf
	v_add_f32_dpp v20, v20, v20 quad_perm:[2,3,0,1] row_mask:0xf bank_mask:0xf
	v_add_f32_dpp v24, v24, v24 quad_perm:[2,3,0,1] row_mask:0xf bank_mask:0xf
	v_add_f32_dpp v28, v28, v28 quad_perm:[2,3,0,1] row_mask:0xf bank_mask:0xf
	v_add_f32_dpp v32, v32, v32 quad_perm:[2,3,0,1] row_mask:0xf bank_mask:0xf
	v_add_f32_dpp v36, v36, v36 quad_perm:[2,3,0,1] row_mask:0xf bank_mask:0xf
	v_add_f32_dpp v52, v52, v52 quad_perm:[2,3,0,1] row_mask:0xf bank_mask:0xf
	s_nop 1
	v_add_f32_dpp v0, v0, v0 row_half_mirror row_mask:0xf bank_mask:0xf
	v_add_f32_dpp v4, v4, v4 row_half_mirror row_mask:0xf bank_mask:0xf
	v_add_f32_dpp v8, v8, v8 row_half_mirror row_mask:0xf bank_mask:0xf
	v_add_f32_dpp v12, v12, v12 row_half_mirror row_mask:0xf bank_mask:0xf
	v_add_f32_dpp v16, v16, v16 row_half_mirror row_mask:0xf bank_mask:0xf
	v_add_f32_dpp v20, v20, v20 row_half_mirror row_mask:0xf bank_mask:0xf
	v_add_f32_dpp v24, v24, v24 row_half_mirror row_mask:0xf bank_mask:0xf
	v_add_f32_dpp v28, v28, v28 row_half_mirror row_mask:0xf bank_mask:0xf
	v_add_f32_dpp v32, v32, v32 row_half_mirror row_mask:0xf bank_mask:0xf
	v_add_f32_dpp v36, v36, v36 row_half_mirror row_mask:0xf bank_mask:0xf
	v_add_f32_dpp v52, v52, v52 row_half_mirror row_mask:0xf bank_mask:0xf
	s_nop 1
	v_add_f32_dpp v0, v0, v0 row_mirror row_mask:0xf bank_mask:0xf
	v_add_f32_dpp v4, v4, v4 row_mirror row_mask:0xf bank_mask:0xf
	v_add_f32_dpp v8, v8, v8 row_mirror row_mask:0xf bank_mask:0xf
	v_add_f32_dpp v12, v12, v12 row_mirror row_mask:0xf bank_mask:0xf
	v_add_f32_dpp v16, v16, v16 row_mirror row_mask:0xf bank_mask:0xf
	v_add_f32_dpp v20, v20, v20 row_mirror row_mask:0xf bank_mask:0xf
	v_add_f32_dpp v24, v24, v24 row_mirror row_mask:0xf bank_mask:0xf
	v_add_f32_dpp v28, v28, v28 row_mirror row_mask:0xf bank_mask:0xf
	v_add_f32_dpp v32, v32, v32 row_mirror row_mask:0xf bank_mask:0xf
	v_add_f32_dpp v36, v36, v36 row_mirror row_mask:0xf bank_mask:0xf
	v_add_f32_dpp v52, v52, v52 row_mirror row_mask:0xf bank_mask:0xf
	s_nop 1
	s_mov_b64 exec, s[98:99]
	ds_write_b32 v48, v0 offset:0
	v_max_f32_e32 v40, v40, v0
	s_mov_b32 s82, 0x10001
; #define LAS __attribute__((address_space(3)))
; DI float bflo(unsigned w) { return __uint_as_float(w << 16); }
; DI float bfhi(unsigned w) { return __uint_as_float(w & 0xffff0000u); }
; DI void attn_sample_unit(const Params& p, int u, const bf16_t* Q, const bf16_t* Kb, const bf16_t* Vb, bf16_t* att, LAS float* sl, int lane) {
;     ...
;     for (int e = 0; e < 9; ++e) { const int pat = e / 3, r = e - 3 * pat; const int dil = 1 << (2 * pat);
;         const int j = lane + 64 * r; const bool valid = j <= 128; const int idx = 2048 + t - dil * (valid ? j : 0);
;         float dot = 0.f;
;         if (idx >= 2048) { const bf16_t* kp = Kb + ((size_t)NP + b * 4 + (idx - 2048)) * 1024 + h * 64;
; #pragma unroll
;             for (int d8 = 0; d8 < 8; ++d8) { const u32x4 kw = *(const u32x4*)(kp + 8 * d8); const f32x4 q0 = *(const LAS f32x4*)(sl + 8 * d8), q1 = *(const LAS f32x4*)(sl + 8 * d8 + 4);
;                 dot += (bflo(kw.x) * q0[0] + bfhi(kw.x) * q0[1]) + (bflo(kw.y) * q0[2] + bfhi(kw.y) * q0[3]) + (bflo(kw.z) * q1[0] + bfhi(kw.z) * q1[1]) + (bflo(kw.w) * q1[2] + bfhi(kw.w) * q1[3]); } }
;         else { const float* kp = ck + (((size_t)b * 2048 + idx) * 16 + h) * 64;
; #pragma unroll
;             for (int d4 = 0; d4 < 16; ++d4) { const f32x4 kv = *(const f32x4*)(kp + 4 * d4); const f32x4 qv = *(const LAS f32x4*)(sl + 4 * d4); dot += (kv[0] * qv[0] + kv[1] * qv[1]) + (kv[2] * qv[2] + kv[3] * qv[3]); } }
;         if (valid) { sl[64 + pat * 192 + j] = dot; mx = fmaxf(mx, dot); } }
	s_mov_b32 s83, 0x10001
	s_mov_b64 exec, s[82:83]
	ds_write_b32 v48, v4 offset:16
	v_max_f32_e32 v40, v40, v4
	ds_write_b32 v48, v8 offset:32
	v_max_f32_e32 v40, v40, v8
	ds_write_b32 v48, v12 offset:48
	v_max_f32_e32 v40, v40, v12
	ds_write_b32 v48, v16 offset:64
	v_max_f32_e32 v40, v40, v16
	ds_write_b32 v48, v20 offset:80
	v_max_f32_e32 v40, v40, v20
	ds_write_b32 v48, v24 offset:96
	v_max_f32_e32 v40, v40, v24
	ds_write_b32 v48, v28 offset:112
	v_max_f32_e32 v40, v40, v28
	ds_write_b32 v48, v32 offset:128
	v_max_f32_e32 v40, v40, v32
	ds_write_b32 v48, v36 offset:144
	v_max_f32_e32 v40, v40, v36
	ds_write_b32 v48, v52 offset:160
	v_max_f32_e32 v40, v40, v52
	s_mov_b64 exec, -1
	s_nop 4
	v_lshlrev_b32_e32 v49, 2, v41
	v_sub_u32_e32 v49, s2, v49
	v_min_i32_e32 v50, 0x7ff, v49
	v_lshl_add_u32 v49, v49, 12, v43
	v_lshl_add_u32 v50, v50, 12, v43
	s_mov_b64 s[76:77], s[84:85]
	global_load_dwordx4 v[0:3], v50, s[76:77]
	s_sub_u32 s76, s76, 0x10000
	s_subb_u32 s77, s77, 0
	global_load_dwordx4 v[4:7], v49, s[76:77]
	s_sub_u32 s76, s76, 0x10000
	s_subb_u32 s77, s77, 0
	global_load_dwordx4 v[8:11], v49, s[76:77]
	s_sub_u32 s76, s76, 0x10000
	s_subb_u32 s77, s77, 0
	global_load_dwordx4 v[12:15], v49, s[76:77]
	s_sub_u32 s76, s76, 0x10000
	s_subb_u32 s77, s77, 0
	global_load_dwordx4 v[16:19], v49, s[76:77]
	s_sub_u32 s76, s76, 0x10000
	s_subb_u32 s77, s77, 0
	global_load_dwordx4 v[20:23], v49, s[76:77]
	s_sub_u32 s76, s76, 0x10000
	s_subb_u32 s77, s77, 0
	global_load_dwordx4 v[24:27], v49, s[76:77]
	s_sub_u32 s76, s76, 0x10000
	s_subb_u32 s77, s77, 0
	global_load_dwordx4 v[28:31], v49, s[76:77]
	s_sub_u32 s76, s76, 0x10000
	s_subb_u32 s77, s77, 0
	global_load_dwordx4 v[32:35], v49, s[76:77]
	s_sub_u32 s76, s76, 0x10000
	s_subb_u32 s77, s77, 0
	global_load_dwordx4 v[36:39], v49, s[76:77]
	s_sub_u32 s76, s76, 0x10000
	s_subb_u32 s77, s77, 0
	global_load_dwordx4 v[52:55], v49, s[76:77]
	s_sub_u32 s76, s76, 0x10000
	s_subb_u32 s77, s77, 0
	s_waitcnt vmcnt(22)
	v_mul_f32_e32 v56, v56, v44
	v_mul_f32_e32 v60, v60, v44
	v_mul_f32_e32 v64, v64, v44
	v_mul_f32_e32 v68, v68, v44
	v_mul_f32_e32 v72, v72, v44
	v_mul_f32_e32 v76, v76, v44
	v_mul_f32_e32 v80, v80, v44
	v_mul_f32_e32 v84, v84, v44
	v_mul_f32_e32 v88, v88, v44
	v_mul_f32_e32 v92, v92, v44
	v_mul_f32_e32 v96, v96, v44
	v_fmac_f32_e32 v56, v57, v45
	v_fmac_f32_e32 v60, v61, v45
	v_fmac_f32_e32 v64, v65, v45
	v_fmac_f32_e32 v68, v69, v45
	v_fmac_f32_e32 v72, v73, v45
	v_fmac_f32_e32 v76, v77, v45
	v_fmac_f32_e32 v80, v81, v45
	v_fmac_f32_e32 v84, v85, v45
	v_fmac_f32_e32 v88, v89, v45
	v_fmac_f32_e32 v92, v93, v45
	v_fmac_f32_e32 v96, v97, v45
	v_fmac_f32_e32 v56, v58, v46
	v_fmac_f32_e32 v60, v62, v46
	v_fmac_f32_e32 v64, v66, v46
	v_fmac_f32_e32 v68, v70, v46
	v_fmac_f32_e32 v72, v74, v46
	v_fmac_f32_e32 v76, v78, v46
	v_fmac_f32_e32 v80, v82, v46
	v_fmac_f32_e32 v84, v86, v46
	v_fmac_f32_e32 v88, v90, v46
	v_fmac_f32_e32 v92, v94, v46
	v_fmac_f32_e32 v96, v98, v46
	v_fmac_f32_e32 v56, v59, v47
	v_fmac_f32_e32 v60, v63, v47
	v_fmac_f32_e32 v64, v67, v47
	v_fmac_f32_e32 v68, v71, v47
	v_fmac_f32_e32 v72, v75, v47
	v_fmac_f32_e32 v76, v79, v47
	v_fmac_f32_e32 v80, v83, v47
	v_fmac_f32_e32 v84, v87, v47
	v_fmac_f32_e32 v88, v91, v47
	v_fmac_f32_e32 v92, v95, v47
	v_fmac_f32_e32 v96, v99, v47
	s_nop 1
	v_add_f32_dpp v56, v56, v56 quad_perm:[1,0,3,2] row_mask:0xf bank_mask:0xf
	v_add_f32_dpp v60, v60, v60 quad_perm:[1,0,3,2] row_mask:0xf bank_mask:0xf
	v_add_f32_dpp v64, v64, v64 quad_perm:[1,0,3,2] row_mask:0xf bank_mask:0xf
	v_add_f32_dpp v68, v68, v68 quad_perm:[1,0,3,2] row_mask:0xf bank_mask:0xf
	v_add_f32_dpp v72, v72, v72 quad_perm:[1,0,3,2] row_mask:0xf bank_mask:0xf
	v_add_f32_dpp v76, v76, v76 quad_perm:[1,0,3,2] row_mask:0xf bank_mask:0xf
	v_add_f32_dpp v80, v80, v80 quad_perm:[1,0,3,2] row_mask:0xf bank_mask:0xf
	v_add_f32_dpp v84, v84, v84 quad_perm:[1,0,3,2] row_mask:0xf bank_mask:0xf
	v_add_f32_dpp v88, v88, v88 quad_perm:[1,0,3,2] row_mask:0xf bank_mask:0xf
	v_add_f32_dpp v92, v92, v92 quad_perm:[1,0,3,2] row_mask:0xf bank_mask:0xf
	v_add_f32_dpp v96, v96, v96 quad_perm:[1,0,3,2] row_mask:0xf bank_mask:0xf
	s_nop 1
	v_add_f32_dpp v56, v56, v56 quad_perm:[2,3,0,1] row_mask:0xf bank_mask:0xf
	v_add_f32_dpp v60, v60, v60 quad_perm:[2,3,0,1] row_mask:0xf bank_mask:0xf
	v_add_f32_dpp v64, v64, v64 quad_perm:[2,3,0,1] row_mask:0xf bank_mask:0xf
	v_add_f32_dpp v68, v68, v68 quad_perm:[2,3,0,1] row_mask:0xf bank_mask:0xf
	v_add_f32_dpp v72, v72, v72 quad_perm:[2,3,0,1] row_mask:0xf bank_mask:0xf
	v_add_f32_dpp v76, v76, v76 quad_perm:[2,3,0,1] row_mask:0xf bank_mask:0xf
	v_add_f32_dpp v80, v80, v80 quad_perm:[2,3,0,1] row_mask:0xf bank_mask:0xf
	v_add_f32_dpp v84, v84, v84 quad_perm:[2,3,0,1] row_mask:0xf bank_mask:0xf
	v_add_f32_dpp v88, v88, v88 quad_perm:[2,3,0,1] row_mask:0xf bank_mask:0xf
	v_add_f32_dpp v92, v92, v92 quad_perm:[2,3,0,1] row_mask:0xf bank_mask:0xf
	v_add_f32_dpp v96, v96, v96 quad_perm:[2,3,0,1] row_mask:0xf bank_mask:0xf
	s_nop 1
	v_add_f32_dpp v56, v56, v56 row_half_mirror row_mask:0xf bank_mask:0xf
	v_add_f32_dpp v60, v60, v60 row_half_mirror row_mask:0xf bank_mask:0xf
	v_add_f32_dpp v64, v64, v64 row_half_mirror row_mask:0xf bank_mask:0xf
	v_add_f32_dpp v68, v68, v68 row_half_mirror row_mask:0xf bank_mask:0xf
	v_add_f32_dpp v72, v72, v72 row_half_mirror row_mask:0xf bank_mask:0xf
	v_add_f32_dpp v76, v76, v76 row_half_mirror row_mask:0xf bank_mask:0xf
	v_add_f32_dpp v80, v80, v80 row_half_mirror row_mask:0xf bank_mask:0xf
	v_add_f32_dpp v84, v84, v84 row_half_mirror row_mask:0xf bank_mask:0xf
	v_add_f32_dpp v88, v88, v88 row_half_mirror row_mask:0xf bank_mask:0xf
; #define LAS __attribute__((address_space(3)))
; DI float bflo(unsigned w) { return __uint_as_float(w << 16); }
; DI float bfhi(unsigned w) { return __uint_as_float(w & 0xffff0000u); }
; DI void attn_sample_unit(const Params& p, int u, const bf16_t* Q, const bf16_t* Kb, const bf16_t* Vb, bf16_t* att, LAS float* sl, int lane) {
;     ...
;     for (int e = 0; e < 9; ++e) { const int pat = e / 3, r = e - 3 * pat; const int dil = 1 << (2 * pat);
;         const int j = lane + 64 * r; const bool valid = j <= 128; const int idx = 2048 + t - dil * (valid ? j : 0);
;         float dot = 0.f;
;         if (idx >= 2048) { const bf16_t* kp = Kb + ((size_t)NP + b * 4 + (idx - 2048)) * 1024 + h * 64;
; #pragma unroll
;             for (int d8 = 0; d8 < 8; ++d8) { const u32x4 kw = *(const u32x4*)(kp + 8 * d8); const f32x4 q0 = *(const LAS f32x4*)(sl + 8 * d8), q1 = *(const LAS f32x4*)(sl + 8 * d8 + 4);
;                 dot += (bflo(kw.x) * q0[0] + bfhi(kw.x) * q0[1]) + (bflo(kw.y) * q0[2] + bfhi(kw.y) * q0[3]) + (bflo(kw.z) * q1[0] + bfhi(kw.z) * q1[1]) + (bflo(kw.w) * q1[2] + bfhi(kw.w) * q1[3]); } }
;         else { const float* kp = ck + (((size_t)b * 2048 + idx) * 16 + h) * 64;
; #pragma unroll
;             for (int d4 = 0; d4 < 16; ++d4) { const f32x4 kv = *(const f32x4*)(kp + 4 * d4); const f32x4 qv = *(const LAS f32x4*)(sl + 4 * d4); dot += (kv[0] * qv[0] + kv[1] * qv[1]) + (kv[2] * qv[2] + kv[3] * qv[3]); } }
;         if (valid) { sl[64 + pat * 192 + j] = dot; mx = fmaxf(mx, dot); } }
	v_add_f32_dpp v92, v92, v92 row_half_mirror row_mask:0xf bank_mask:0xf
	v_add_f32_dpp v96, v96, v96 row_half_mirror row_mask:0xf bank_mask:0xf
	s_nop 1
	v_add_f32_dpp v56, v56, v56 row_mirror row_mask:0xf bank_mask:0xf
	v_add_f32_dpp v60, v60, v60 row_mirror row_mask:0xf bank_mask:0xf
	v_add_f32_dpp v64, v64, v64 row_mirror row_mask:0xf bank_mask:0xf
	v_add_f32_dpp v68, v68, v68 row_mirror row_mask:0xf bank_mask:0xf
	v_add_f32_dpp v72, v72, v72 row_mirror row_mask:0xf bank_mask:0xf
	v_add_f32_dpp v76, v76, v76 row_mirror row_mask:0xf bank_mask:0xf
	v_add_f32_dpp v80, v80, v80 row_mirror row_mask:0xf bank_mask:0xf
	v_add_f32_dpp v84, v84, v84 row_mirror row_mask:0xf bank_mask:0xf
	v_add_f32_dpp v88, v88, v88 row_mirror row_mask:0xf bank_mask:0xf
	v_add_f32_dpp v92, v92, v92 row_mirror row_mask:0xf bank_mask:0xf
	v_add_f32_dpp v96, v96, v96 row_mirror row_mask:0xf bank_mask:0xf
	s_nop 1
	s_mov_b32 s82, 0x10001
	s_mov_b32 s83, 0x10001
	s_mov_b64 exec, s[82:83]
	ds_write_b32 v48, v56 offset:176
	v_max_f32_e32 v40, v40, v56
	ds_write_b32 v48, v60 offset:192
	v_max_f32_e32 v40, v40, v60
	ds_write_b32 v48, v64 offset:208
	v_max_f32_e32 v40, v40, v64
	ds_write_b32 v48, v68 offset:224
	v_max_f32_e32 v40, v40, v68
	ds_write_b32 v48, v72 offset:240
	v_max_f32_e32 v40, v40, v72
	ds_write_b32 v48, v76 offset:256
	v_max_f32_e32 v40, v40, v76
	ds_write_b32 v48, v80 offset:272
	v_max_f32_e32 v40, v40, v80
	ds_write_b32 v48, v84 offset:288
	v_max_f32_e32 v40, v40, v84
	ds_write_b32 v48, v88 offset:304
	v_max_f32_e32 v40, v40, v88
	ds_write_b32 v48, v92 offset:320
	v_max_f32_e32 v40, v40, v92
	ds_write_b32 v48, v96 offset:336
	v_max_f32_e32 v40, v40, v96
	s_mov_b64 exec, -1
	s_nop 4
	global_load_dwordx4 v[56:59], v49, s[76:77]
	s_sub_u32 s76, s76, 0x10000
	s_subb_u32 s77, s77, 0
	global_load_dwordx4 v[60:63], v49, s[76:77]
	s_sub_u32 s76, s76, 0x10000
	s_subb_u32 s77, s77, 0
	global_load_dwordx4 v[64:67], v49, s[76:77]
	s_sub_u32 s76, s76, 0x10000
	s_subb_u32 s77, s77, 0
	global_load_dwordx4 v[68:71], v49, s[76:77]
	s_sub_u32 s76, s76, 0x10000
	s_subb_u32 s77, s77, 0
	global_load_dwordx4 v[72:75], v49, s[76:77]
	s_sub_u32 s76, s76, 0x10000
	s_subb_u32 s77, s77, 0
	global_load_dwordx4 v[76:79], v49, s[76:77]
	s_sub_u32 s76, s76, 0x10000
	s_subb_u32 s77, s77, 0
	global_load_dwordx4 v[80:83], v49, s[76:77]
	s_sub_u32 s76, s76, 0x10000
	s_subb_u32 s77, s77, 0
	global_load_dwordx4 v[84:87], v49, s[76:77]
	s_sub_u32 s76, s76, 0x10000
	s_subb_u32 s77, s77, 0
	global_load_dwordx4 v[88:91], v49, s[76:77]
	s_sub_u32 s76, s76, 0x10000
	s_subb_u32 s77, s77, 0
	global_load_dwordx4 v[92:95], v49, s[76:77]
	s_sub_u32 s76, s76, 0x10000
	s_subb_u32 s77, s77, 0
	global_load_dwordx4 v[96:99], v49, s[76:77]
	s_sub_u32 s76, s76, 0x10000
	s_subb_u32 s77, s77, 0
	s_waitcnt vmcnt(22)
	v_mul_f32_e32 v110, v110, v44
	v_mul_f32_e32 v114, v114, v44
	v_mul_f32_e32 v118, v118, v44
	v_mul_f32_e32 v122, v122, v44
	v_mul_f32_e32 v214, v214, v44
	v_mul_f32_e32 v218, v218, v44
	v_mul_f32_e32 v222, v222, v44
	v_mul_f32_e32 v226, v226, v44
	v_mul_f32_e32 v230, v230, v44
	v_mul_f32_e32 v234, v234, v44
	v_mul_f32_e32 v238, v238, v44
	v_fmac_f32_e32 v110, v111, v45
	v_fmac_f32_e32 v114, v115, v45
	v_fmac_f32_e32 v118, v119, v45
	v_fmac_f32_e32 v122, v123, v45
	v_fmac_f32_e32 v214, v215, v45
	v_fmac_f32_e32 v218, v219, v45
	v_fmac_f32_e32 v222, v223, v45
	v_fmac_f32_e32 v226, v227, v45
	v_fmac_f32_e32 v230, v231, v45
	v_fmac_f32_e32 v234, v235, v45
	v_fmac_f32_e32 v238, v239, v45
	v_fmac_f32_e32 v110, v112, v46
	v_fmac_f32_e32 v114, v116, v46
	v_fmac_f32_e32 v118, v120, v46
	v_fmac_f32_e32 v122, v124, v46
	v_fmac_f32_e32 v214, v216, v46
	v_fmac_f32_e32 v218, v220, v46
	v_fmac_f32_e32 v222, v224, v46
	v_fmac_f32_e32 v226, v228, v46
	v_fmac_f32_e32 v230, v232, v46
	v_fmac_f32_e32 v234, v236, v46
	v_fmac_f32_e32 v238, v240, v46
	v_fmac_f32_e32 v110, v113, v47
	v_fmac_f32_e32 v114, v117, v47
	v_fmac_f32_e32 v118, v121, v47
	v_fmac_f32_e32 v122, v125, v47
	v_fmac_f32_e32 v214, v217, v47
	v_fmac_f32_e32 v218, v221, v47
	v_fmac_f32_e32 v222, v225, v47
	v_fmac_f32_e32 v226, v229, v47
	v_fmac_f32_e32 v230, v233, v47
	v_fmac_f32_e32 v234, v237, v47
	v_fmac_f32_e32 v238, v241, v47
	s_nop 1
	v_add_f32_dpp v110, v110, v110 quad_perm:[1,0,3,2] row_mask:0xf bank_mask:0xf
	v_add_f32_dpp v114, v114, v114 quad_perm:[1,0,3,2] row_mask:0xf bank_mask:0xf
	v_add_f32_dpp v118, v118, v118 quad_perm:[1,0,3,2] row_mask:0xf bank_mask:0xf
	v_add_f32_dpp v122, v122, v122 quad_perm:[1,0,3,2] row_mask:0xf bank_mask:0xf
	v_add_f32_dpp v214, v214, v214 quad_perm:[1,0,3,2] row_mask:0xf bank_mask:0xf
	v_add_f32_dpp v218, v218, v218 quad_perm:[1,0,3,2] row_mask:0xf bank_mask:0xf
	v_add_f32_dpp v222, v222, v222 quad_perm:[1,0,3,2] row_mask:0xf bank_mask:0xf
	v_add_f32_dpp v226, v226, v226 quad_perm:[1,0,3,2] row_mask:0xf bank_mask:0xf
	v_add_f32_dpp v230, v230, v230 quad_perm:[1,0,3,2] row_mask:0xf bank_mask:0xf
	v_add_f32_dpp v234, v234, v234 quad_perm:[1,0,3,2] row_mask:0xf bank_mask:0xf
	v_add_f32_dpp v238, v238, v238 quad_perm:[1,0,3,2] row_mask:0xf bank_mask:0xf
	s_nop 1
	v_add_f32_dpp v110, v110, v110 quad_perm:[2,3,0,1] row_mask:0xf bank_mask:0xf
	v_add_f32_dpp v114, v114, v114 quad_perm:[2,3,0,1] row_mask:0xf bank_mask:0xf
	v_add_f32_dpp v118, v118, v118 quad_perm:[2,3,0,1] row_mask:0xf bank_mask:0xf
	v_add_f32_dpp v122, v122, v122 quad_perm:[2,3,0,1] row_mask:0xf bank_mask:0xf
	v_add_f32_dpp v214, v214, v214 quad_perm:[2,3,0,1] row_mask:0xf bank_mask:0xf
	v_add_f32_dpp v218, v218, v218 quad_perm:[2,3,0,1] row_mask:0xf bank_mask:0xf
	v_add_f32_dpp v222, v222, v222 quad_perm:[2,3,0,1] row_mask:0xf bank_mask:0xf
; #define LAS __attribute__((address_space(3)))
; DI float bflo(unsigned w) { return __uint_as_float(w << 16); }
; DI float bfhi(unsigned w) { return __uint_as_float(w & 0xffff0000u); }
; DI void attn_sample_unit(const Params& p, int u, const bf16_t* Q, const bf16_t* Kb, const bf16_t* Vb, bf16_t* att, LAS float* sl, int lane) {
;     ...
;     for (int e = 0; e < 9; ++e) { const int pat = e / 3, r = e - 3 * pat; const int dil = 1 << (2 * pat);
;         const int j = lane + 64 * r; const bool valid = j <= 128; const int idx = 2048 + t - dil * (valid ? j : 0);
;         float dot = 0.f;
;         if (idx >= 2048) { const bf16_t* kp = Kb + ((size_t)NP + b * 4 + (idx - 2048)) * 1024 + h * 64;
; #pragma unroll
;             for (int d8 = 0; d8 < 8; ++d8) { const u32x4 kw = *(const u32x4*)(kp + 8 * d8); const f32x4 q0 = *(const LAS f32x4*)(sl + 8 * d8), q1 = *(const LAS f32x4*)(sl + 8 * d8 + 4);
;                 dot += (bflo(kw.x) * q0[0] + bfhi(kw.x) * q0[1]) + (bflo(kw.y) * q0[2] + bfhi(kw.y) * q0[3]) + (bflo(kw.z) * q1[0] + bfhi(kw.z) * q1[1]) + (bflo(kw.w) * q1[2] + bfhi(kw.w) * q1[3]); } }
;         else { const float* kp = ck + (((size_t)b * 2048 + idx) * 16 + h) * 64;
; #pragma unroll
;             for (int d4 = 0; d4 < 16; ++d4) { const f32x4 kv = *(const f32x4*)(kp + 4 * d4); const f32x4 qv = *(const LAS f32x4*)(sl + 4 * d4); dot += (kv[0] * qv[0] + kv[1] * qv[1]) + (kv[2] * qv[2] + kv[3] * qv[3]); } }
;         if (valid) { sl[64 + pat * 192 + j] = dot; mx = fmaxf(mx, dot); } }
	v_add_f32_dpp v226, v226, v226 quad_perm:[2,3,0,1] row_mask:0xf bank_mask:0xf
	v_add_f32_dpp v230, v230, v230 quad_perm:[2,3,0,1] row_mask:0xf bank_mask:0xf
	v_add_f32_dpp v234, v234, v234 quad_perm:[2,3,0,1] row_mask:0xf bank_mask:0xf
	v_add_f32_dpp v238, v238, v238 quad_perm:[2,3,0,1] row_mask:0xf bank_mask:0xf
	s_nop 1
	v_add_f32_dpp v110, v110, v110 row_half_mirror row_mask:0xf bank_mask:0xf
	v_add_f32_dpp v114, v114, v114 row_half_mirror row_mask:0xf bank_mask:0xf
	v_add_f32_dpp v118, v118, v118 row_half_mirror row_mask:0xf bank_mask:0xf
	v_add_f32_dpp v122, v122, v122 row_half_mirror row_mask:0xf bank_mask:0xf
	v_add_f32_dpp v214, v214, v214 row_half_mirror row_mask:0xf bank_mask:0xf
	v_add_f32_dpp v218, v218, v218 row_half_mirror row_mask:0xf bank_mask:0xf
	v_add_f32_dpp v222, v222, v222 row_half_mirror row_mask:0xf bank_mask:0xf
	v_add_f32_dpp v226, v226, v226 row_half_mirror row_mask:0xf bank_mask:0xf
	v_add_f32_dpp v230, v230, v230 row_half_mirror row_mask:0xf bank_mask:0xf
	v_add_f32_dpp v234, v234, v234 row_half_mirror row_mask:0xf bank_mask:0xf
	v_add_f32_dpp v238, v238, v238 row_half_mirror row_mask:0xf bank_mask:0xf
	s_nop 1
	v_add_f32_dpp v110, v110, v110 row_mirror row_mask:0xf bank_mask:0xf
	v_add_f32_dpp v114, v114, v114 row_mirror row_mask:0xf bank_mask:0xf
	v_add_f32_dpp v118, v118, v118 row_mirror row_mask:0xf bank_mask:0xf
	v_add_f32_dpp v122, v122, v122 row_mirror row_mask:0xf bank_mask:0xf
	v_add_f32_dpp v214, v214, v214 row_mirror row_mask:0xf bank_mask:0xf
	v_add_f32_dpp v218, v218, v218 row_mirror row_mask:0xf bank_mask:0xf
	v_add_f32_dpp v222, v222, v222 row_mirror row_mask:0xf bank_mask:0xf
	v_add_f32_dpp v226, v226, v226 row_mirror row_mask:0xf bank_mask:0xf
	v_add_f32_dpp v230, v230, v230 row_mirror row_mask:0xf bank_mask:0xf
	v_add_f32_dpp v234, v234, v234 row_mirror row_mask:0xf bank_mask:0xf
	v_add_f32_dpp v238, v238, v238 row_mirror row_mask:0xf bank_mask:0xf
	s_nop 1
	s_mov_b32 s82, 0x10001
	s_mov_b32 s83, 0x10001
	s_mov_b64 exec, s[82:83]
	ds_write_b32 v48, v110 offset:352
	v_max_f32_e32 v40, v40, v110
	ds_write_b32 v48, v114 offset:368
	v_max_f32_e32 v40, v40, v114
	ds_write_b32 v48, v118 offset:384
	v_max_f32_e32 v40, v40, v118
	ds_write_b32 v48, v122 offset:400
	v_max_f32_e32 v40, v40, v122
	ds_write_b32 v48, v214 offset:416
	v_max_f32_e32 v40, v40, v214
	ds_write_b32 v48, v218 offset:432
	v_max_f32_e32 v40, v40, v218
	ds_write_b32 v48, v222 offset:448
	v_max_f32_e32 v40, v40, v222
	ds_write_b32 v48, v226 offset:464
	v_max_f32_e32 v40, v40, v226
	ds_write_b32 v48, v230 offset:480
	v_max_f32_e32 v40, v40, v230
	ds_write_b32 v48, v234 offset:496
	v_max_f32_e32 v40, v40, v234
	s_mov_b64 exec, 1
	ds_write_b32 v48, v238 offset:512
	v_max_f32_e32 v40, v40, v238
	s_mov_b64 exec, -1
	s_nop 4
	global_load_dwordx4 v[110:113], v49, s[76:77]
	s_sub_u32 s76, s76, 0x10000
	s_subb_u32 s77, s77, 0
	global_load_dwordx4 v[114:117], v49, s[76:77]
	s_sub_u32 s76, s76, 0x10000
	s_subb_u32 s77, s77, 0
	global_load_dwordx4 v[118:121], v49, s[76:77]
	s_sub_u32 s76, s76, 0x10000
	s_subb_u32 s77, s77, 0
	global_load_dwordx4 v[122:125], v49, s[76:77]
	s_sub_u32 s76, s76, 0x10000
	s_subb_u32 s77, s77, 0
	global_load_dwordx4 v[214:217], v49, s[76:77]
	s_sub_u32 s76, s76, 0x10000
	s_subb_u32 s77, s77, 0
	global_load_dwordx4 v[218:221], v49, s[76:77]
	s_sub_u32 s76, s76, 0x10000
	s_subb_u32 s77, s77, 0
	global_load_dwordx4 v[222:225], v49, s[76:77]
	s_sub_u32 s76, s76, 0x10000
	s_subb_u32 s77, s77, 0
	global_load_dwordx4 v[226:229], v49, s[76:77]
	s_sub_u32 s76, s76, 0x10000
	s_subb_u32 s77, s77, 0
	global_load_dwordx4 v[230:233], v49, s[76:77]
	s_sub_u32 s76, s76, 0x10000
	s_subb_u32 s77, s77, 0
	global_load_dwordx4 v[234:237], v49, s[76:77]
	s_sub_u32 s76, s76, 0x10000
	s_subb_u32 s77, s77, 0
	s_mov_b64 exec, 0xffff
	global_load_dwordx4 v[238:241], v49, s[76:77]
	s_mov_b64 exec, -1
	s_waitcnt vmcnt(22)
	v_mul_f32_e32 v0, v0, v44
	v_mul_f32_e32 v4, v4, v44
	v_mul_f32_e32 v8, v8, v44
	v_mul_f32_e32 v12, v12, v44
	v_mul_f32_e32 v16, v16, v44
	v_mul_f32_e32 v20, v20, v44
	v_mul_f32_e32 v24, v24, v44
	v_mul_f32_e32 v28, v28, v44
	v_mul_f32_e32 v32, v32, v44
	v_mul_f32_e32 v36, v36, v44
	v_mul_f32_e32 v52, v52, v44
	v_fmac_f32_e32 v0, v1, v45
	v_fmac_f32_e32 v4, v5, v45
	v_fmac_f32_e32 v8, v9, v45
	v_fmac_f32_e32 v12, v13, v45
	v_fmac_f32_e32 v16, v17, v45
	v_fmac_f32_e32 v20, v21, v45
	v_fmac_f32_e32 v24, v25, v45
	v_fmac_f32_e32 v28, v29, v45
	v_fmac_f32_e32 v32, v33, v45
	v_fmac_f32_e32 v36, v37, v45
	v_fmac_f32_e32 v52, v53, v45
	v_fmac_f32_e32 v0, v2, v46
	v_fmac_f32_e32 v4, v6, v46
	v_fmac_f32_e32 v8, v10, v46
	v_fmac_f32_e32 v12, v14, v46
	v_fmac_f32_e32 v16, v18, v46
	v_fmac_f32_e32 v20, v22, v46
	v_fmac_f32_e32 v24, v26, v46
	v_fmac_f32_e32 v28, v30, v46
	v_fmac_f32_e32 v32, v34, v46
	v_fmac_f32_e32 v36, v38, v46
	v_fmac_f32_e32 v52, v54, v46
	v_fmac_f32_e32 v0, v3, v47
	v_fmac_f32_e32 v4, v7, v47
	v_fmac_f32_e32 v8, v11, v47
	v_fmac_f32_e32 v12, v15, v47
	v_fmac_f32_e32 v16, v19, v47
	v_fmac_f32_e32 v20, v23, v47
	v_fmac_f32_e32 v24, v27, v47
	v_fmac_f32_e32 v28, v31, v47
	v_fmac_f32_e32 v32, v35, v47
	v_fmac_f32_e32 v36, v39, v47
	v_fmac_f32_e32 v52, v55, v47
	s_nop 1
	v_add_f32_dpp v0, v0, v0 quad_perm:[1,0,3,2] row_mask:0xf bank_mask:0xf
	v_add_f32_dpp v4, v4, v4 quad_perm:[1,0,3,2] row_mask:0xf bank_mask:0xf
	v_add_f32_dpp v8, v8, v8 quad_perm:[1,0,3,2] row_mask:0xf bank_mask:0xf
	v_add_f32_dpp v12, v12, v12 quad_perm:[1,0,3,2] row_mask:0xf bank_mask:0xf
	v_add_f32_dpp v16, v16, v16 quad_perm:[1,0,3,2] row_mask:0xf bank_mask:0xf
	v_add_f32_dpp v20, v20, v20 quad_perm:[1,0,3,2] row_mask:0xf bank_mask:0xf
; #define LAS __attribute__((address_space(3)))
; DI float bflo(unsigned w) { return __uint_as_float(w << 16); }
; DI float bfhi(unsigned w) { return __uint_as_float(w & 0xffff0000u); }
; DI void attn_sample_unit(const Params& p, int u, const bf16_t* Q, const bf16_t* Kb, const bf16_t* Vb, bf16_t* att, LAS float* sl, int lane) {
;     ...
;     for (int e = 0; e < 9; ++e) { const int pat = e / 3, r = e - 3 * pat; const int dil = 1 << (2 * pat);
;         const int j = lane + 64 * r; const bool valid = j <= 128; const int idx = 2048 + t - dil * (valid ? j : 0);
;         float dot = 0.f;
;         if (idx >= 2048) { const bf16_t* kp = Kb + ((size_t)NP + b * 4 + (idx - 2048)) * 1024 + h * 64;
; #pragma unroll
;             for (int d8 = 0; d8 < 8; ++d8) { const u32x4 kw = *(const u32x4*)(kp + 8 * d8); const f32x4 q0 = *(const LAS f32x4*)(sl + 8 * d8), q1 = *(const LAS f32x4*)(sl + 8 * d8 + 4);
;                 dot += (bflo(kw.x) * q0[0] + bfhi(kw.x) * q0[1]) + (bflo(kw.y) * q0[2] + bfhi(kw.y) * q0[3]) + (bflo(kw.z) * q1[0] + bfhi(kw.z) * q1[1]) + (bflo(kw.w) * q1[2] + bfhi(kw.w) * q1[3]); } }
;         else { const float* kp = ck + (((size_t)b * 2048 + idx) * 16 + h) * 64;
; #pragma unroll
;             for (int d4 = 0; d4 < 16; ++d4) { const f32x4 kv = *(const f32x4*)(kp + 4 * d4); const f32x4 qv = *(const LAS f32x4*)(sl + 4 * d4); dot += (kv[0] * qv[0] + kv[1] * qv[1]) + (kv[2] * qv[2] + kv[3] * qv[3]); } }
;         if (valid) { sl[64 + pat * 192 + j] = dot; mx = fmaxf(mx, dot); } }
	v_add_f32_dpp v24, v24, v24 quad_perm:[1,0,3,2] row_mask:0xf bank_mask:0xf
	v_add_f32_dpp v28, v28, v28 quad_perm:[1,0,3,2] row_mask:0xf bank_mask:0xf
	v_add_f32_dpp v32, v32, v32 quad_perm:[1,0,3,2] row_mask:0xf bank_mask:0xf
	v_add_f32_dpp v36, v36, v36 quad_perm:[1,0,3,2] row_mask:0xf bank_mask:0xf
	v_add_f32_dpp v52, v52, v52 quad_perm:[1,0,3,2] row_mask:0xf bank_mask:0xf
	s_nop 1
	v_add_f32_dpp v0, v0, v0 quad_perm:[2,3,0,1] row_mask:0xf bank_mask:0xf
	v_add_f32_dpp v4, v4, v4 quad_perm:[2,3,0,1] row_mask:0xf bank_mask:0xf
	v_add_f32_dpp v8, v8, v8 quad_perm:[2,3,0,1] row_mask:0xf bank_mask:0xf
	v_add_f32_dpp v12, v12, v12 quad_perm:[2,3,0,1] row_mask:0xf bank_mask:0xf
	v_add_f32_dpp v16, v16, v16 quad_perm:[2,3,0,1] row_mask:0xf bank_mask:0xf
	v_add_f32_dpp v20, v20, v20 quad_perm:[2,3,0,1] row_mask:0xf bank_mask:0xf
	v_add_f32_dpp v24, v24, v24 quad_perm:[2,3,0,1] row_mask:0xf bank_mask:0xf
	v_add_f32_dpp v28, v28, v28 quad_perm:[2,3,0,1] row_mask:0xf bank_mask:0xf
	v_add_f32_dpp v32, v32, v32 quad_perm:[2,3,0,1] row_mask:0xf bank_mask:0xf
	v_add_f32_dpp v36, v36, v36 quad_perm:[2,3,0,1] row_mask:0xf bank_mask:0xf
	v_add_f32_dpp v52, v52, v52 quad_perm:[2,3,0,1] row_mask:0xf bank_mask:0xf
	s_nop 1
	v_add_f32_dpp v0, v0, v0 row_half_mirror row_mask:0xf bank_mask:0xf
	v_add_f32_dpp v4, v4, v4 row_half_mirror row_mask:0xf bank_mask:0xf
	v_add_f32_dpp v8, v8, v8 row_half_mirror row_mask:0xf bank_mask:0xf
	v_add_f32_dpp v12, v12, v12 row_half_mirror row_mask:0xf bank_mask:0xf
	v_add_f32_dpp v16, v16, v16 row_half_mirror row_mask:0xf bank_mask:0xf
	v_add_f32_dpp v20, v20, v20 row_half_mirror row_mask:0xf bank_mask:0xf
	v_add_f32_dpp v24, v24, v24 row_half_mirror row_mask:0xf bank_mask:0xf
	v_add_f32_dpp v28, v28, v28 row_half_mirror row_mask:0xf bank_mask:0xf
	v_add_f32_dpp v32, v32, v32 row_half_mirror row_mask:0xf bank_mask:0xf
	v_add_f32_dpp v36, v36, v36 row_half_mirror row_mask:0xf bank_mask:0xf
	v_add_f32_dpp v52, v52, v52 row_half_mirror row_mask:0xf bank_mask:0xf
	s_nop 1
	v_add_f32_dpp v0, v0, v0 row_mirror row_mask:0xf bank_mask:0xf
	v_add_f32_dpp v4, v4, v4 row_mirror row_mask:0xf bank_mask:0xf
	v_add_f32_dpp v8, v8, v8 row_mirror row_mask:0xf bank_mask:0xf
	v_add_f32_dpp v12, v12, v12 row_mirror row_mask:0xf bank_mask:0xf
	v_add_f32_dpp v16, v16, v16 row_mirror row_mask:0xf bank_mask:0xf
	v_add_f32_dpp v20, v20, v20 row_mirror row_mask:0xf bank_mask:0xf
	v_add_f32_dpp v24, v24, v24 row_mirror row_mask:0xf bank_mask:0xf
	v_add_f32_dpp v28, v28, v28 row_mirror row_mask:0xf bank_mask:0xf
	v_add_f32_dpp v32, v32, v32 row_mirror row_mask:0xf bank_mask:0xf
	v_add_f32_dpp v36, v36, v36 row_mirror row_mask:0xf bank_mask:0xf
	v_add_f32_dpp v52, v52, v52 row_mirror row_mask:0xf bank_mask:0xf
	s_nop 1
	s_mov_b32 s82, 0x10000
	s_mov_b32 s83, 0x10001
	s_mov_b64 exec, s[82:83]
	ds_write_b32 v48, v0 offset:768
	v_max_f32_e32 v40, v40, v0
	s_mov_b32 s82, 0x10001
	s_mov_b32 s83, 0x10001
	s_mov_b64 exec, s[82:83]
	ds_write_b32 v48, v4 offset:784
	v_max_f32_e32 v40, v40, v4
	ds_write_b32 v48, v8 offset:800
	v_max_f32_e32 v40, v40, v8
	ds_write_b32 v48, v12 offset:816
	v_max_f32_e32 v40, v40, v12
	ds_write_b32 v48, v16 offset:832
	v_max_f32_e32 v40, v40, v16
	ds_write_b32 v48, v20 offset:848
	v_max_f32_e32 v40, v40, v20
	ds_write_b32 v48, v24 offset:864
	v_max_f32_e32 v40, v40, v24
	ds_write_b32 v48, v28 offset:880
	v_max_f32_e32 v40, v40, v28
	ds_write_b32 v48, v32 offset:896
	v_max_f32_e32 v40, v40, v32
	ds_write_b32 v48, v36 offset:912
	v_max_f32_e32 v40, v40, v36
	ds_write_b32 v48, v52 offset:928
	v_max_f32_e32 v40, v40, v52
	s_mov_b64 exec, -1
	s_nop 4
	v_lshlrev_b32_e32 v49, 4, v41
	v_sub_u32_e32 v49, s2, v49
	v_min_i32_e32 v50, 0x7ff, v49
	v_lshl_add_u32 v49, v49, 12, v43
	v_lshl_add_u32 v50, v50, 12, v43
	s_mov_b64 s[76:77], s[84:85]
	global_load_dwordx4 v[0:3], v50, s[76:77]
	s_sub_u32 s76, s76, 0x40000
	s_subb_u32 s77, s77, 0
	global_load_dwordx4 v[4:7], v49, s[76:77]
	s_sub_u32 s76, s76, 0x40000
	s_subb_u32 s77, s77, 0
	global_load_dwordx4 v[8:11], v49, s[76:77]
	s_sub_u32 s76, s76, 0x40000
	s_subb_u32 s77, s77, 0
	global_load_dwordx4 v[12:15], v49, s[76:77]
	s_sub_u32 s76, s76, 0x40000
	s_subb_u32 s77, s77, 0
	global_load_dwordx4 v[16:19], v49, s[76:77]
	s_sub_u32 s76, s76, 0x40000
	s_subb_u32 s77, s77, 0
	global_load_dwordx4 v[20:23], v49, s[76:77]
	s_sub_u32 s76, s76, 0x40000
	s_subb_u32 s77, s77, 0
	global_load_dwordx4 v[24:27], v49, s[76:77]
	s_sub_u32 s76, s76, 0x40000
	s_subb_u32 s77, s77, 0
	global_load_dwordx4 v[28:31], v49, s[76:77]
	s_sub_u32 s76, s76, 0x40000
	s_subb_u32 s77, s77, 0
	global_load_dwordx4 v[32:35], v49, s[76:77]
	s_sub_u32 s76, s76, 0x40000
	s_subb_u32 s77, s77, 0
	global_load_dwordx4 v[36:39], v49, s[76:77]
	s_sub_u32 s76, s76, 0x40000
	s_subb_u32 s77, s77, 0
	global_load_dwordx4 v[52:55], v49, s[76:77]
	s_sub_u32 s76, s76, 0x40000
	s_subb_u32 s77, s77, 0
	s_waitcnt vmcnt(22)
; #define LAS __attribute__((address_space(3)))
; DI float bflo(unsigned w) { return __uint_as_float(w << 16); }
; DI float bfhi(unsigned w) { return __uint_as_float(w & 0xffff0000u); }
; DI void attn_sample_unit(const Params& p, int u, const bf16_t* Q, const bf16_t* Kb, const bf16_t* Vb, bf16_t* att, LAS float* sl, int lane) {
;     ...
;     for (int e = 0; e < 9; ++e) { const int pat = e / 3, r = e - 3 * pat; const int dil = 1 << (2 * pat);
;         const int j = lane + 64 * r; const bool valid = j <= 128; const int idx = 2048 + t - dil * (valid ? j : 0);
;         float dot = 0.f;
;         if (idx >= 2048) { const bf16_t* kp = Kb + ((size_t)NP + b * 4 + (idx - 2048)) * 1024 + h * 64;
; #pragma unroll
;             for (int d8 = 0; d8 < 8; ++d8) { const u32x4 kw = *(const u32x4*)(kp + 8 * d8); const f32x4 q0 = *(const LAS f32x4*)(sl + 8 * d8), q1 = *(const LAS f32x4*)(sl + 8 * d8 + 4);
;                 dot += (bflo(kw.x) * q0[0] + bfhi(kw.x) * q0[1]) + (bflo(kw.y) * q0[2] + bfhi(kw.y) * q0[3]) + (bflo(kw.z) * q1[0] + bfhi(kw.z) * q1[1]) + (bflo(kw.w) * q1[2] + bfhi(kw.w) * q1[3]); } }
;         else { const float* kp = ck + (((size_t)b * 2048 + idx) * 16 + h) * 64;
; #pragma unroll
;             for (int d4 = 0; d4 < 16; ++d4) { const f32x4 kv = *(const f32x4*)(kp + 4 * d4); const f32x4 qv = *(const LAS f32x4*)(sl + 4 * d4); dot += (kv[0] * qv[0] + kv[1] * qv[1]) + (kv[2] * qv[2] + kv[3] * qv[3]); } }
;         if (valid) { sl[64 + pat * 192 + j] = dot; mx = fmaxf(mx, dot); } }
	v_mul_f32_e32 v56, v56, v44
	v_mul_f32_e32 v60, v60, v44
	v_mul_f32_e32 v64, v64, v44
	v_mul_f32_e32 v68, v68, v44
	v_mul_f32_e32 v72, v72, v44
	v_mul_f32_e32 v76, v76, v44
	v_mul_f32_e32 v80, v80, v44
	v_mul_f32_e32 v84, v84, v44
	v_mul_f32_e32 v88, v88, v44
	v_mul_f32_e32 v92, v92, v44
	v_mul_f32_e32 v96, v96, v44
	v_fmac_f32_e32 v56, v57, v45
	v_fmac_f32_e32 v60, v61, v45
	v_fmac_f32_e32 v64, v65, v45
	v_fmac_f32_e32 v68, v69, v45
	v_fmac_f32_e32 v72, v73, v45
	v_fmac_f32_e32 v76, v77, v45
	v_fmac_f32_e32 v80, v81, v45
	v_fmac_f32_e32 v84, v85, v45
	v_fmac_f32_e32 v88, v89, v45
	v_fmac_f32_e32 v92, v93, v45
	v_fmac_f32_e32 v96, v97, v45
	v_fmac_f32_e32 v56, v58, v46
	v_fmac_f32_e32 v60, v62, v46
	v_fmac_f32_e32 v64, v66, v46
	v_fmac_f32_e32 v68, v70, v46
	v_fmac_f32_e32 v72, v74, v46
	v_fmac_f32_e32 v76, v78, v46
	v_fmac_f32_e32 v80, v82, v46
	v_fmac_f32_e32 v84, v86, v46
	v_fmac_f32_e32 v88, v90, v46
	v_fmac_f32_e32 v92, v94, v46
	v_fmac_f32_e32 v96, v98, v46
	v_fmac_f32_e32 v56, v59, v47
	v_fmac_f32_e32 v60, v63, v47
	v_fmac_f32_e32 v64, v67, v47
	v_fmac_f32_e32 v68, v71, v47
	v_fmac_f32_e32 v72, v75, v47
	v_fmac_f32_e32 v76, v79, v47
	v_fmac_f32_e32 v80, v83, v47
	v_fmac_f32_e32 v84, v87, v47
	v_fmac_f32_e32 v88, v91, v47
	v_fmac_f32_e32 v92, v95, v47
	v_fmac_f32_e32 v96, v99, v47
	s_nop 1
	v_add_f32_dpp v56, v56, v56 quad_perm:[1,0,3,2] row_mask:0xf bank_mask:0xf
	v_add_f32_dpp v60, v60, v60 quad_perm:[1,0,3,2] row_mask:0xf bank_mask:0xf
	v_add_f32_dpp v64, v64, v64 quad_perm:[1,0,3,2] row_mask:0xf bank_mask:0xf
	v_add_f32_dpp v68, v68, v68 quad_perm:[1,0,3,2] row_mask:0xf bank_mask:0xf
	v_add_f32_dpp v72, v72, v72 quad_perm:[1,0,3,2] row_mask:0xf bank_mask:0xf
	v_add_f32_dpp v76, v76, v76 quad_perm:[1,0,3,2] row_mask:0xf bank_mask:0xf
	v_add_f32_dpp v80, v80, v80 quad_perm:[1,0,3,2] row_mask:0xf bank_mask:0xf
	v_add_f32_dpp v84, v84, v84 quad_perm:[1,0,3,2] row_mask:0xf bank_mask:0xf
	v_add_f32_dpp v88, v88, v88 quad_perm:[1,0,3,2] row_mask:0xf bank_mask:0xf
	v_add_f32_dpp v92, v92, v92 quad_perm:[1,0,3,2] row_mask:0xf bank_mask:0xf
	v_add_f32_dpp v96, v96, v96 quad_perm:[1,0,3,2] row_mask:0xf bank_mask:0xf
	s_nop 1
	v_add_f32_dpp v56, v56, v56 quad_perm:[2,3,0,1] row_mask:0xf bank_mask:0xf
	v_add_f32_dpp v60, v60, v60 quad_perm:[2,3,0,1] row_mask:0xf bank_mask:0xf
	v_add_f32_dpp v64, v64, v64 quad_perm:[2,3,0,1] row_mask:0xf bank_mask:0xf
	v_add_f32_dpp v68, v68, v68 quad_perm:[2,3,0,1] row_mask:0xf bank_mask:0xf
	v_add_f32_dpp v72, v72, v72 quad_perm:[2,3,0,1] row_mask:0xf bank_mask:0xf
	v_add_f32_dpp v76, v76, v76 quad_perm:[2,3,0,1] row_mask:0xf bank_mask:0xf
	v_add_f32_dpp v80, v80, v80 quad_perm:[2,3,0,1] row_mask:0xf bank_mask:0xf
	v_add_f32_dpp v84, v84, v84 quad_perm:[2,3,0,1] row_mask:0xf bank_mask:0xf
	v_add_f32_dpp v88, v88, v88 quad_perm:[2,3,0,1] row_mask:0xf bank_mask:0xf
	v_add_f32_dpp v92, v92, v92 quad_perm:[2,3,0,1] row_mask:0xf bank_mask:0xf
	v_add_f32_dpp v96, v96, v96 quad_perm:[2,3,0,1] row_mask:0xf bank_mask:0xf
	s_nop 1
	v_add_f32_dpp v56, v56, v56 row_half_mirror row_mask:0xf bank_mask:0xf
	v_add_f32_dpp v60, v60, v60 row_half_mirror row_mask:0xf bank_mask:0xf
	v_add_f32_dpp v64, v64, v64 row_half_mirror row_mask:0xf bank_mask:0xf
	v_add_f32_dpp v68, v68, v68 row_half_mirror row_mask:0xf bank_mask:0xf
	v_add_f32_dpp v72, v72, v72 row_half_mirror row_mask:0xf bank_mask:0xf
	v_add_f32_dpp v76, v76, v76 row_half_mirror row_mask:0xf bank_mask:0xf
	v_add_f32_dpp v80, v80, v80 row_half_mirror row_mask:0xf bank_mask:0xf
	v_add_f32_dpp v84, v84, v84 row_half_mirror row_mask:0xf bank_mask:0xf
	v_add_f32_dpp v88, v88, v88 row_half_mirror row_mask:0xf bank_mask:0xf
	v_add_f32_dpp v92, v92, v92 row_half_mirror row_mask:0xf bank_mask:0xf
	v_add_f32_dpp v96, v96, v96 row_half_mirror row_mask:0xf bank_mask:0xf
	s_nop 1
	v_add_f32_dpp v56, v56, v56 row_mirror row_mask:0xf bank_mask:0xf
	v_add_f32_dpp v60, v60, v60 row_mirror row_mask:0xf bank_mask:0xf
	v_add_f32_dpp v64, v64, v64 row_mirror row_mask:0xf bank_mask:0xf
	v_add_f32_dpp v68, v68, v68 row_mirror row_mask:0xf bank_mask:0xf
	v_add_f32_dpp v72, v72, v72 row_mirror row_mask:0xf bank_mask:0xf
	v_add_f32_dpp v76, v76, v76 row_mirror row_mask:0xf bank_mask:0xf
	v_add_f32_dpp v80, v80, v80 row_mirror row_mask:0xf bank_mask:0xf
	v_add_f32_dpp v84, v84, v84 row_mirror row_mask:0xf bank_mask:0xf
	v_add_f32_dpp v88, v88, v88 row_mirror row_mask:0xf bank_mask:0xf
	v_add_f32_dpp v92, v92, v92 row_mirror row_mask:0xf bank_mask:0xf
	v_add_f32_dpp v96, v96, v96 row_mirror row_mask:0xf bank_mask:0xf
	s_nop 1
	s_mov_b32 s82, 0x10001
	s_mov_b32 s83, 0x10001
	s_mov_b64 exec, s[82:83]
	ds_write_b32 v48, v56 offset:944
	v_max_f32_e32 v40, v40, v56
	ds_write_b32 v48, v60 offset:960
	v_max_f32_e32 v40, v40, v60
	ds_write_b32 v48, v64 offset:976
	v_max_f32_e32 v40, v40, v64
	ds_write_b32 v48, v68 offset:992
	v_max_f32_e32 v40, v40, v68
	ds_write_b32 v48, v72 offset:1008
	v_max_f32_e32 v40, v40, v72
	ds_write_b32 v48, v76 offset:1024
	v_max_f32_e32 v40, v40, v76
	ds_write_b32 v48, v80 offset:1040
	v_max_f32_e32 v40, v40, v80
	ds_write_b32 v48, v84 offset:1056
	v_max_f32_e32 v40, v40, v84
	ds_write_b32 v48, v88 offset:1072
	v_max_f32_e32 v40, v40, v88
	ds_write_b32 v48, v92 offset:1088
	v_max_f32_e32 v40, v40, v92
	ds_write_b32 v48, v96 offset:1104
	v_max_f32_e32 v40, v40, v96
	s_mov_b64 exec, -1
	s_nop 4
	global_load_dwordx4 v[56:59], v49, s[76:77]
	s_sub_u32 s76, s76, 0x40000
	s_subb_u32 s77, s77, 0
	global_load_dwordx4 v[60:63], v49, s[76:77]
	s_sub_u32 s76, s76, 0x40000
	s_subb_u32 s77, s77, 0
	global_load_dwordx4 v[64:67], v49, s[76:77]
	s_sub_u32 s76, s76, 0x40000
	s_subb_u32 s77, s77, 0
	global_load_dwordx4 v[68:71], v49, s[76:77]
	s_sub_u32 s76, s76, 0x40000
	s_subb_u32 s77, s77, 0
	global_load_dwordx4 v[72:75], v49, s[76:77]
	s_sub_u32 s76, s76, 0x40000
	s_subb_u32 s77, s77, 0
	global_load_dwordx4 v[76:79], v49, s[76:77]
	s_sub_u32 s76, s76, 0x40000
	s_subb_u32 s77, s77, 0
	global_load_dwordx4 v[80:83], v49, s[76:77]
	s_sub_u32 s76, s76, 0x40000
	s_subb_u32 s77, s77, 0
	global_load_dwordx4 v[84:87], v49, s[76:77]
	s_sub_u32 s76, s76, 0x40000
	s_subb_u32 s77, s77, 0
	global_load_dwordx4 v[88:91], v49, s[76:77]
	s_sub_u32 s76, s76, 0x40000
	s_subb_u32 s77, s77, 0
	global_load_dwordx4 v[92:95], v49, s[76:77]
	s_sub_u32 s76, s76, 0x40000
	s_subb_u32 s77, s77, 0
	global_load_dwordx4 v[96:99], v49, s[76:77]
	s_sub_u32 s76, s76, 0x40000
	s_subb_u32 s77, s77, 0
	s_waitcnt vmcnt(22)
; #define LAS __attribute__((address_space(3)))
; DI float bflo(unsigned w) { return __uint_as_float(w << 16); }
; DI float bfhi(unsigned w) { return __uint_as_float(w & 0xffff0000u); }
; DI void attn_sample_unit(const Params& p, int u, const bf16_t* Q, const bf16_t* Kb, const bf16_t* Vb, bf16_t* att, LAS float* sl, int lane) {
;     ...
;     for (int e = 0; e < 9; ++e) { const int pat = e / 3, r = e - 3 * pat; const int dil = 1 << (2 * pat);
;         const int j = lane + 64 * r; const bool valid = j <= 128; const int idx = 2048 + t - dil * (valid ? j : 0);
;         float dot = 0.f;
;         if (idx >= 2048) { const bf16_t* kp = Kb + ((size_t)NP + b * 4 + (idx - 2048)) * 1024 + h * 64;
; #pragma unroll
;             for (int d8 = 0; d8 < 8; ++d8) { const u32x4 kw = *(const u32x4*)(kp + 8 * d8); const f32x4 q0 = *(const LAS f32x4*)(sl + 8 * d8), q1 = *(const LAS f32x4*)(sl + 8 * d8 + 4);
;                 dot += (bflo(kw.x) * q0[0] + bfhi(kw.x) * q0[1]) + (bflo(kw.y) * q0[2] + bfhi(kw.y) * q0[3]) + (bflo(kw.z) * q1[0] + bfhi(kw.z) * q1[1]) + (bflo(kw.w) * q1[2] + bfhi(kw.w) * q1[3]); } }
;         else { const float* kp = ck + (((size_t)b * 2048 + idx) * 16 + h) * 64;
; #pragma unroll
;             for (int d4 = 0; d4 < 16; ++d4) { const f32x4 kv = *(const f32x4*)(kp + 4 * d4); const f32x4 qv = *(const LAS f32x4*)(sl + 4 * d4); dot += (kv[0] * qv[0] + kv[1] * qv[1]) + (kv[2] * qv[2] + kv[3] * qv[3]); } }
;         if (valid) { sl[64 + pat * 192 + j] = dot; mx = fmaxf(mx, dot); } }
	v_mul_f32_e32 v110, v110, v44
	v_mul_f32_e32 v114, v114, v44
	v_mul_f32_e32 v118, v118, v44
	v_mul_f32_e32 v122, v122, v44
	v_mul_f32_e32 v214, v214, v44
	v_mul_f32_e32 v218, v218, v44
	v_mul_f32_e32 v222, v222, v44
	v_mul_f32_e32 v226, v226, v44
	v_mul_f32_e32 v230, v230, v44
	v_mul_f32_e32 v234, v234, v44
	v_mul_f32_e32 v238, v238, v44
	v_fmac_f32_e32 v110, v111, v45
	v_fmac_f32_e32 v114, v115, v45
	v_fmac_f32_e32 v118, v119, v45
	v_fmac_f32_e32 v122, v123, v45
	v_fmac_f32_e32 v214, v215, v45
	v_fmac_f32_e32 v218, v219, v45
	v_fmac_f32_e32 v222, v223, v45
	v_fmac_f32_e32 v226, v227, v45
	v_fmac_f32_e32 v230, v231, v45
	v_fmac_f32_e32 v234, v235, v45
	v_fmac_f32_e32 v238, v239, v45
	v_fmac_f32_e32 v110, v112, v46
	v_fmac_f32_e32 v114, v116, v46
	v_fmac_f32_e32 v118, v120, v46
	v_fmac_f32_e32 v122, v124, v46
	v_fmac_f32_e32 v214, v216, v46
	v_fmac_f32_e32 v218, v220, v46
	v_fmac_f32_e32 v222, v224, v46
	v_fmac_f32_e32 v226, v228, v46
	v_fmac_f32_e32 v230, v232, v46
	v_fmac_f32_e32 v234, v236, v46
	v_fmac_f32_e32 v238, v240, v46
	v_fmac_f32_e32 v110, v113, v47
	v_fmac_f32_e32 v114, v117, v47
	v_fmac_f32_e32 v118, v121, v47
	v_fmac_f32_e32 v122, v125, v47
	v_fmac_f32_e32 v214, v217, v47
	v_fmac_f32_e32 v218, v221, v47
	v_fmac_f32_e32 v222, v225, v47
	v_fmac_f32_e32 v226, v229, v47
	v_fmac_f32_e32 v230, v233, v47
	v_fmac_f32_e32 v234, v237, v47
	v_fmac_f32_e32 v238, v241, v47
	s_nop 1
	v_add_f32_dpp v110, v110, v110 quad_perm:[1,0,3,2] row_mask:0xf bank_mask:0xf
	v_add_f32_dpp v114, v114, v114 quad_perm:[1,0,3,2] row_mask:0xf bank_mask:0xf
	v_add_f32_dpp v118, v118, v118 quad_perm:[1,0,3,2] row_mask:0xf bank_mask:0xf
	v_add_f32_dpp v122, v122, v122 quad_perm:[1,0,3,2] row_mask:0xf bank_mask:0xf
	v_add_f32_dpp v214, v214, v214 quad_perm:[1,0,3,2] row_mask:0xf bank_mask:0xf
	v_add_f32_dpp v218, v218, v218 quad_perm:[1,0,3,2] row_mask:0xf bank_mask:0xf
	v_add_f32_dpp v222, v222, v222 quad_perm:[1,0,3,2] row_mask:0xf bank_mask:0xf
	v_add_f32_dpp v226, v226, v226 quad_perm:[1,0,3,2] row_mask:0xf bank_mask:0xf
	v_add_f32_dpp v230, v230, v230 quad_perm:[1,0,3,2] row_mask:0xf bank_mask:0xf
	v_add_f32_dpp v234, v234, v234 quad_perm:[1,0,3,2] row_mask:0xf bank_mask:0xf
	v_add_f32_dpp v238, v238, v238 quad_perm:[1,0,3,2] row_mask:0xf bank_mask:0xf
	s_nop 1
	v_add_f32_dpp v110, v110, v110 quad_perm:[2,3,0,1] row_mask:0xf bank_mask:0xf
	v_add_f32_dpp v114, v114, v114 quad_perm:[2,3,0,1] row_mask:0xf bank_mask:0xf
	v_add_f32_dpp v118, v118, v118 quad_perm:[2,3,0,1] row_mask:0xf bank_mask:0xf
	v_add_f32_dpp v122, v122, v122 quad_perm:[2,3,0,1] row_mask:0xf bank_mask:0xf
	v_add_f32_dpp v214, v214, v214 quad_perm:[2,3,0,1] row_mask:0xf bank_mask:0xf
	v_add_f32_dpp v218, v218, v218 quad_perm:[2,3,0,1] row_mask:0xf bank_mask:0xf
	v_add_f32_dpp v222, v222, v222 quad_perm:[2,3,0,1] row_mask:0xf bank_mask:0xf
	v_add_f32_dpp v226, v226, v226 quad_perm:[2,3,0,1] row_mask:0xf bank_mask:0xf
	v_add_f32_dpp v230, v230, v230 quad_perm:[2,3,0,1] row_mask:0xf bank_mask:0xf
	v_add_f32_dpp v234, v234, v234 quad_perm:[2,3,0,1] row_mask:0xf bank_mask:0xf
	v_add_f32_dpp v238, v238, v238 quad_perm:[2,3,0,1] row_mask:0xf bank_mask:0xf
	s_nop 1
	v_add_f32_dpp v110, v110, v110 row_half_mirror row_mask:0xf bank_mask:0xf
	v_add_f32_dpp v114, v114, v114 row_half_mirror row_mask:0xf bank_mask:0xf
	v_add_f32_dpp v118, v118, v118 row_half_mirror row_mask:0xf bank_mask:0xf
	v_add_f32_dpp v122, v122, v122 row_half_mirror row_mask:0xf bank_mask:0xf
	v_add_f32_dpp v214, v214, v214 row_half_mirror row_mask:0xf bank_mask:0xf
	v_add_f32_dpp v218, v218, v218 row_half_mirror row_mask:0xf bank_mask:0xf
	v_add_f32_dpp v222, v222, v222 row_half_mirror row_mask:0xf bank_mask:0xf
	v_add_f32_dpp v226, v226, v226 row_half_mirror row_mask:0xf bank_mask:0xf
	v_add_f32_dpp v230, v230, v230 row_half_mirror row_mask:0xf bank_mask:0xf
	v_add_f32_dpp v234, v234, v234 row_half_mirror row_mask:0xf bank_mask:0xf
	v_add_f32_dpp v238, v238, v238 row_half_mirror row_mask:0xf bank_mask:0xf
	s_nop 1
	v_add_f32_dpp v110, v110, v110 row_mirror row_mask:0xf bank_mask:0xf
	v_add_f32_dpp v114, v114, v114 row_mirror row_mask:0xf bank_mask:0xf
	v_add_f32_dpp v118, v118, v118 row_mirror row_mask:0xf bank_mask:0xf
	v_add_f32_dpp v122, v122, v122 row_mirror row_mask:0xf bank_mask:0xf
	v_add_f32_dpp v214, v214, v214 row_mirror row_mask:0xf bank_mask:0xf
	v_add_f32_dpp v218, v218, v218 row_mirror row_mask:0xf bank_mask:0xf
	v_add_f32_dpp v222, v222, v222 row_mirror row_mask:0xf bank_mask:0xf
	v_add_f32_dpp v226, v226, v226 row_mirror row_mask:0xf bank_mask:0xf
	v_add_f32_dpp v230, v230, v230 row_mirror row_mask:0xf bank_mask:0xf
	v_add_f32_dpp v234, v234, v234 row_mirror row_mask:0xf bank_mask:0xf
	v_add_f32_dpp v238, v238, v238 row_mirror row_mask:0xf bank_mask:0xf
	s_nop 1
	s_mov_b32 s82, 0x10001
	s_mov_b32 s83, 0x10001
	s_mov_b64 exec, s[82:83]
	ds_write_b32 v48, v110 offset:1120
	v_max_f32_e32 v40, v40, v110
	ds_write_b32 v48, v114 offset:1136
	v_max_f32_e32 v40, v40, v114
	ds_write_b32 v48, v118 offset:1152
	v_max_f32_e32 v40, v40, v118
	ds_write_b32 v48, v122 offset:1168
	v_max_f32_e32 v40, v40, v122
	ds_write_b32 v48, v214 offset:1184
	v_max_f32_e32 v40, v40, v214
	ds_write_b32 v48, v218 offset:1200
	v_max_f32_e32 v40, v40, v218
	ds_write_b32 v48, v222 offset:1216
	v_max_f32_e32 v40, v40, v222
	ds_write_b32 v48, v226 offset:1232
	v_max_f32_e32 v40, v40, v226
	ds_write_b32 v48, v230 offset:1248
	v_max_f32_e32 v40, v40, v230
	ds_write_b32 v48, v234 offset:1264
	v_max_f32_e32 v40, v40, v234
	s_mov_b64 exec, 1
	ds_write_b32 v48, v238 offset:1280
	v_max_f32_e32 v40, v40, v238
	s_mov_b64 exec, -1
	s_nop 4
	global_load_dwordx4 v[110:113], v49, s[76:77]
	s_sub_u32 s76, s76, 0x40000
	s_subb_u32 s77, s77, 0
	global_load_dwordx4 v[114:117], v49, s[76:77]
	s_sub_u32 s76, s76, 0x40000
	s_subb_u32 s77, s77, 0
	global_load_dwordx4 v[118:121], v49, s[76:77]
	s_sub_u32 s76, s76, 0x40000
	s_subb_u32 s77, s77, 0
	global_load_dwordx4 v[122:125], v49, s[76:77]
	s_sub_u32 s76, s76, 0x40000
	s_subb_u32 s77, s77, 0
	global_load_dwordx4 v[214:217], v49, s[76:77]
	s_sub_u32 s76, s76, 0x40000
	s_subb_u32 s77, s77, 0
	global_load_dwordx4 v[218:221], v49, s[76:77]
	s_sub_u32 s76, s76, 0x40000
	s_subb_u32 s77, s77, 0
	global_load_dwordx4 v[222:225], v49, s[76:77]
	s_sub_u32 s76, s76, 0x40000
	s_subb_u32 s77, s77, 0
	global_load_dwordx4 v[226:229], v49, s[76:77]
	s_sub_u32 s76, s76, 0x40000
	s_subb_u32 s77, s77, 0
	global_load_dwordx4 v[230:233], v49, s[76:77]
	s_sub_u32 s76, s76, 0x40000
	s_subb_u32 s77, s77, 0
	global_load_dwordx4 v[234:237], v49, s[76:77]
	s_sub_u32 s76, s76, 0x40000
	s_subb_u32 s77, s77, 0
	s_mov_b64 exec, 0xffff
	global_load_dwordx4 v[238:241], v49, s[76:77]
	s_mov_b64 exec, -1
	s_waitcnt vmcnt(22)
; #define LAS __attribute__((address_space(3)))
; DI float bflo(unsigned w) { return __uint_as_float(w << 16); }
; DI float bfhi(unsigned w) { return __uint_as_float(w & 0xffff0000u); }
; DI void attn_sample_unit(const Params& p, int u, const bf16_t* Q, const bf16_t* Kb, const bf16_t* Vb, bf16_t* att, LAS float* sl, int lane) {
;     ...
;     for (int e = 0; e < 9; ++e) { const int pat = e / 3, r = e - 3 * pat; const int dil = 1 << (2 * pat);
;         const int j = lane + 64 * r; const bool valid = j <= 128; const int idx = 2048 + t - dil * (valid ? j : 0);
;         float dot = 0.f;
;         if (idx >= 2048) { const bf16_t* kp = Kb + ((size_t)NP + b * 4 + (idx - 2048)) * 1024 + h * 64;
; #pragma unroll
;             for (int d8 = 0; d8 < 8; ++d8) { const u32x4 kw = *(const u32x4*)(kp + 8 * d8); const f32x4 q0 = *(const LAS f32x4*)(sl + 8 * d8), q1 = *(const LAS f32x4*)(sl + 8 * d8 + 4);
;                 dot += (bflo(kw.x) * q0[0] + bfhi(kw.x) * q0[1]) + (bflo(kw.y) * q0[2] + bfhi(kw.y) * q0[3]) + (bflo(kw.z) * q1[0] + bfhi(kw.z) * q1[1]) + (bflo(kw.w) * q1[2] + bfhi(kw.w) * q1[3]); } }
;         else { const float* kp = ck + (((size_t)b * 2048 + idx) * 16 + h) * 64;
; #pragma unroll
;             for (int d4 = 0; d4 < 16; ++d4) { const f32x4 kv = *(const f32x4*)(kp + 4 * d4); const f32x4 qv = *(const LAS f32x4*)(sl + 4 * d4); dot += (kv[0] * qv[0] + kv[1] * qv[1]) + (kv[2] * qv[2] + kv[3] * qv[3]); } }
;         if (valid) { sl[64 + pat * 192 + j] = dot; mx = fmaxf(mx, dot); } }
;     mx = wave_max(mx);
	v_mul_f32_e32 v0, v0, v44
	v_mul_f32_e32 v4, v4, v44
	v_mul_f32_e32 v8, v8, v44
	v_mul_f32_e32 v12, v12, v44
	v_mul_f32_e32 v16, v16, v44
	v_mul_f32_e32 v20, v20, v44
	v_mul_f32_e32 v24, v24, v44
	v_mul_f32_e32 v28, v28, v44
	v_mul_f32_e32 v32, v32, v44
	v_mul_f32_e32 v36, v36, v44
	v_mul_f32_e32 v52, v52, v44
	v_fmac_f32_e32 v0, v1, v45
	v_fmac_f32_e32 v4, v5, v45
	v_fmac_f32_e32 v8, v9, v45
	v_fmac_f32_e32 v12, v13, v45
	v_fmac_f32_e32 v16, v17, v45
	v_fmac_f32_e32 v20, v21, v45
	v_fmac_f32_e32 v24, v25, v45
	v_fmac_f32_e32 v28, v29, v45
	v_fmac_f32_e32 v32, v33, v45
	v_fmac_f32_e32 v36, v37, v45
	v_fmac_f32_e32 v52, v53, v45
	v_fmac_f32_e32 v0, v2, v46
	v_fmac_f32_e32 v4, v6, v46
	v_fmac_f32_e32 v8, v10, v46
	v_fmac_f32_e32 v12, v14, v46
	v_fmac_f32_e32 v16, v18, v46
	v_fmac_f32_e32 v20, v22, v46
	v_fmac_f32_e32 v24, v26, v46
	v_fmac_f32_e32 v28, v30, v46
	v_fmac_f32_e32 v32, v34, v46
	v_fmac_f32_e32 v36, v38, v46
	v_fmac_f32_e32 v52, v54, v46
	v_fmac_f32_e32 v0, v3, v47
	v_fmac_f32_e32 v4, v7, v47
	v_fmac_f32_e32 v8, v11, v47
	v_fmac_f32_e32 v12, v15, v47
	v_fmac_f32_e32 v16, v19, v47
	v_fmac_f32_e32 v20, v23, v47
	v_fmac_f32_e32 v24, v27, v47
	v_fmac_f32_e32 v28, v31, v47
	v_fmac_f32_e32 v32, v35, v47
	v_fmac_f32_e32 v36, v39, v47
	v_fmac_f32_e32 v52, v55, v47
	s_nop 1
	v_add_f32_dpp v0, v0, v0 quad_perm:[1,0,3,2] row_mask:0xf bank_mask:0xf
	v_add_f32_dpp v4, v4, v4 quad_perm:[1,0,3,2] row_mask:0xf bank_mask:0xf
	v_add_f32_dpp v8, v8, v8 quad_perm:[1,0,3,2] row_mask:0xf bank_mask:0xf
	v_add_f32_dpp v12, v12, v12 quad_perm:[1,0,3,2] row_mask:0xf bank_mask:0xf
	v_add_f32_dpp v16, v16, v16 quad_perm:[1,0,3,2] row_mask:0xf bank_mask:0xf
	v_add_f32_dpp v20, v20, v20 quad_perm:[1,0,3,2] row_mask:0xf bank_mask:0xf
	v_add_f32_dpp v24, v24, v24 quad_perm:[1,0,3,2] row_mask:0xf bank_mask:0xf
	v_add_f32_dpp v28, v28, v28 quad_perm:[1,0,3,2] row_mask:0xf bank_mask:0xf
	v_add_f32_dpp v32, v32, v32 quad_perm:[1,0,3,2] row_mask:0xf bank_mask:0xf
	v_add_f32_dpp v36, v36, v36 quad_perm:[1,0,3,2] row_mask:0xf bank_mask:0xf
	v_add_f32_dpp v52, v52, v52 quad_perm:[1,0,3,2] row_mask:0xf bank_mask:0xf
	s_nop 1
	v_add_f32_dpp v0, v0, v0 quad_perm:[2,3,0,1] row_mask:0xf bank_mask:0xf
	v_add_f32_dpp v4, v4, v4 quad_perm:[2,3,0,1] row_mask:0xf bank_mask:0xf
	v_add_f32_dpp v8, v8, v8 quad_perm:[2,3,0,1] row_mask:0xf bank_mask:0xf
	v_add_f32_dpp v12, v12, v12 quad_perm:[2,3,0,1] row_mask:0xf bank_mask:0xf
	v_add_f32_dpp v16, v16, v16 quad_perm:[2,3,0,1] row_mask:0xf bank_mask:0xf
	v_add_f32_dpp v20, v20, v20 quad_perm:[2,3,0,1] row_mask:0xf bank_mask:0xf
	v_add_f32_dpp v24, v24, v24 quad_perm:[2,3,0,1] row_mask:0xf bank_mask:0xf
	v_add_f32_dpp v28, v28, v28 quad_perm:[2,3,0,1] row_mask:0xf bank_mask:0xf
	v_add_f32_dpp v32, v32, v32 quad_perm:[2,3,0,1] row_mask:0xf bank_mask:0xf
	v_add_f32_dpp v36, v36, v36 quad_perm:[2,3,0,1] row_mask:0xf bank_mask:0xf
	v_add_f32_dpp v52, v52, v52 quad_perm:[2,3,0,1] row_mask:0xf bank_mask:0xf
	s_nop 1
	v_add_f32_dpp v0, v0, v0 row_half_mirror row_mask:0xf bank_mask:0xf
	v_add_f32_dpp v4, v4, v4 row_half_mirror row_mask:0xf bank_mask:0xf
	v_add_f32_dpp v8, v8, v8 row_half_mirror row_mask:0xf bank_mask:0xf
	v_add_f32_dpp v12, v12, v12 row_half_mirror row_mask:0xf bank_mask:0xf
	v_add_f32_dpp v16, v16, v16 row_half_mirror row_mask:0xf bank_mask:0xf
	v_add_f32_dpp v20, v20, v20 row_half_mirror row_mask:0xf bank_mask:0xf
	v_add_f32_dpp v24, v24, v24 row_half_mirror row_mask:0xf bank_mask:0xf
	v_add_f32_dpp v28, v28, v28 row_half_mirror row_mask:0xf bank_mask:0xf
	v_add_f32_dpp v32, v32, v32 row_half_mirror row_mask:0xf bank_mask:0xf
	v_add_f32_dpp v36, v36, v36 row_half_mirror row_mask:0xf bank_mask:0xf
	v_add_f32_dpp v52, v52, v52 row_half_mirror row_mask:0xf bank_mask:0xf
	s_nop 1
	v_add_f32_dpp v0, v0, v0 row_mirror row_mask:0xf bank_mask:0xf
	v_add_f32_dpp v4, v4, v4 row_mirror row_mask:0xf bank_mask:0xf
	v_add_f32_dpp v8, v8, v8 row_mirror row_mask:0xf bank_mask:0xf
	v_add_f32_dpp v12, v12, v12 row_mirror row_mask:0xf bank_mask:0xf
	v_add_f32_dpp v16, v16, v16 row_mirror row_mask:0xf bank_mask:0xf
	v_add_f32_dpp v20, v20, v20 row_mirror row_mask:0xf bank_mask:0xf
	v_add_f32_dpp v24, v24, v24 row_mirror row_mask:0xf bank_mask:0xf
	v_add_f32_dpp v28, v28, v28 row_mirror row_mask:0xf bank_mask:0xf
	v_add_f32_dpp v32, v32, v32 row_mirror row_mask:0xf bank_mask:0xf
	v_add_f32_dpp v36, v36, v36 row_mirror row_mask:0xf bank_mask:0xf
	v_add_f32_dpp v52, v52, v52 row_mirror row_mask:0xf bank_mask:0xf
	s_nop 1
	s_mov_b32 s82, 0x10000
	s_mov_b32 s83, 0x10001
	s_mov_b64 exec, s[82:83]
	ds_write_b32 v48, v0 offset:1536
	v_max_f32_e32 v40, v40, v0
	s_mov_b32 s82, 0x10001
	s_mov_b32 s83, 0x10001
	s_mov_b64 exec, s[82:83]
	ds_write_b32 v48, v4 offset:1552
	v_max_f32_e32 v40, v40, v4
	ds_write_b32 v48, v8 offset:1568
	v_max_f32_e32 v40, v40, v8
	ds_write_b32 v48, v12 offset:1584
	v_max_f32_e32 v40, v40, v12
	ds_write_b32 v48, v16 offset:1600
	v_max_f32_e32 v40, v40, v16
	ds_write_b32 v48, v20 offset:1616
	v_max_f32_e32 v40, v40, v20
	ds_write_b32 v48, v24 offset:1632
	v_max_f32_e32 v40, v40, v24
	ds_write_b32 v48, v28 offset:1648
	v_max_f32_e32 v40, v40, v28
	ds_write_b32 v48, v32 offset:1664
	v_max_f32_e32 v40, v40, v32
	ds_write_b32 v48, v36 offset:1680
	v_max_f32_e32 v40, v40, v36
	ds_write_b32 v48, v52 offset:1696
	v_max_f32_e32 v40, v40, v52
	s_mov_b64 exec, -1
	s_nop 4
	s_waitcnt vmcnt(11)
; #define LAS __attribute__((address_space(3)))
; DI float bflo(unsigned w) { return __uint_as_float(w << 16); }
; DI float bfhi(unsigned w) { return __uint_as_float(w & 0xffff0000u); }
; DI void attn_sample_unit(const Params& p, int u, const bf16_t* Q, const bf16_t* Kb, const bf16_t* Vb, bf16_t* att, LAS float* sl, int lane) {
;     ...
;     for (int e = 0; e < 9; ++e) { const int pat = e / 3, r = e - 3 * pat; const int dil = 1 << (2 * pat);
;         const int j = lane + 64 * r; const bool valid = j <= 128; const int idx = 2048 + t - dil * (valid ? j : 0);
;         float dot = 0.f;
;         if (idx >= 2048) { const bf16_t* kp = Kb + ((size_t)NP + b * 4 + (idx - 2048)) * 1024 + h * 64;
; #pragma unroll
;             for (int d8 = 0; d8 < 8; ++d8) { const u32x4 kw = *(const u32x4*)(kp + 8 * d8); const f32x4 q0 = *(const LAS f32x4*)(sl + 8 * d8), q1 = *(const LAS f32x4*)(sl + 8 * d8 + 4);
;                 dot += (bflo(kw.x) * q0[0] + bfhi(kw.x) * q0[1]) + (bflo(kw.y) * q0[2] + bfhi(kw.y) * q0[3]) + (bflo(kw.z) * q1[0] + bfhi(kw.z) * q1[1]) + (bflo(kw.w) * q1[2] + bfhi(kw.w) * q1[3]); } }
;         else { const float* kp = ck + (((size_t)b * 2048 + idx) * 16 + h) * 64;
; #pragma unroll
;             for (int d4 = 0; d4 < 16; ++d4) { const f32x4 kv = *(const f32x4*)(kp + 4 * d4); const f32x4 qv = *(const LAS f32x4*)(sl + 4 * d4); dot += (kv[0] * qv[0] + kv[1] * qv[1]) + (kv[2] * qv[2] + kv[3] * qv[3]); } }
;         if (valid) { sl[64 + pat * 192 + j] = dot; mx = fmaxf(mx, dot); } }
;     mx = wave_max(mx);
	v_mul_f32_e32 v56, v56, v44
	v_mul_f32_e32 v60, v60, v44
	v_mul_f32_e32 v64, v64, v44
	v_mul_f32_e32 v68, v68, v44
	v_mul_f32_e32 v72, v72, v44
	v_mul_f32_e32 v76, v76, v44
	v_mul_f32_e32 v80, v80, v44
	v_mul_f32_e32 v84, v84, v44
	v_mul_f32_e32 v88, v88, v44
	v_mul_f32_e32 v92, v92, v44
	v_mul_f32_e32 v96, v96, v44
	v_fmac_f32_e32 v56, v57, v45
	v_fmac_f32_e32 v60, v61, v45
	v_fmac_f32_e32 v64, v65, v45
	v_fmac_f32_e32 v68, v69, v45
	v_fmac_f32_e32 v72, v73, v45
	v_fmac_f32_e32 v76, v77, v45
	v_fmac_f32_e32 v80, v81, v45
	v_fmac_f32_e32 v84, v85, v45
	v_fmac_f32_e32 v88, v89, v45
	v_fmac_f32_e32 v92, v93, v45
	v_fmac_f32_e32 v96, v97, v45
	v_fmac_f32_e32 v56, v58, v46
	v_fmac_f32_e32 v60, v62, v46
	v_fmac_f32_e32 v64, v66, v46
	v_fmac_f32_e32 v68, v70, v46
	v_fmac_f32_e32 v72, v74, v46
	v_fmac_f32_e32 v76, v78, v46
	v_fmac_f32_e32 v80, v82, v46
	v_fmac_f32_e32 v84, v86, v46
	v_fmac_f32_e32 v88, v90, v46
	v_fmac_f32_e32 v92, v94, v46
	v_fmac_f32_e32 v96, v98, v46
	v_fmac_f32_e32 v56, v59, v47
	v_fmac_f32_e32 v60, v63, v47
	v_fmac_f32_e32 v64, v67, v47
	v_fmac_f32_e32 v68, v71, v47
	v_fmac_f32_e32 v72, v75, v47
	v_fmac_f32_e32 v76, v79, v47
	v_fmac_f32_e32 v80, v83, v47
	v_fmac_f32_e32 v84, v87, v47
	v_fmac_f32_e32 v88, v91, v47
	v_fmac_f32_e32 v92, v95, v47
	v_fmac_f32_e32 v96, v99, v47
	s_nop 1
	v_add_f32_dpp v56, v56, v56 quad_perm:[1,0,3,2] row_mask:0xf bank_mask:0xf
	v_add_f32_dpp v60, v60, v60 quad_perm:[1,0,3,2] row_mask:0xf bank_mask:0xf
	v_add_f32_dpp v64, v64, v64 quad_perm:[1,0,3,2] row_mask:0xf bank_mask:0xf
	v_add_f32_dpp v68, v68, v68 quad_perm:[1,0,3,2] row_mask:0xf bank_mask:0xf
	v_add_f32_dpp v72, v72, v72 quad_perm:[1,0,3,2] row_mask:0xf bank_mask:0xf
	v_add_f32_dpp v76, v76, v76 quad_perm:[1,0,3,2] row_mask:0xf bank_mask:0xf
	v_add_f32_dpp v80, v80, v80 quad_perm:[1,0,3,2] row_mask:0xf bank_mask:0xf
	v_add_f32_dpp v84, v84, v84 quad_perm:[1,0,3,2] row_mask:0xf bank_mask:0xf
	v_add_f32_dpp v88, v88, v88 quad_perm:[1,0,3,2] row_mask:0xf bank_mask:0xf
	v_add_f32_dpp v92, v92, v92 quad_perm:[1,0,3,2] row_mask:0xf bank_mask:0xf
	v_add_f32_dpp v96, v96, v96 quad_perm:[1,0,3,2] row_mask:0xf bank_mask:0xf
	s_nop 1
	v_add_f32_dpp v56, v56, v56 quad_perm:[2,3,0,1] row_mask:0xf bank_mask:0xf
	v_add_f32_dpp v60, v60, v60 quad_perm:[2,3,0,1] row_mask:0xf bank_mask:0xf
	v_add_f32_dpp v64, v64, v64 quad_perm:[2,3,0,1] row_mask:0xf bank_mask:0xf
	v_add_f32_dpp v68, v68, v68 quad_perm:[2,3,0,1] row_mask:0xf bank_mask:0xf
	v_add_f32_dpp v72, v72, v72 quad_perm:[2,3,0,1] row_mask:0xf bank_mask:0xf
	v_add_f32_dpp v76, v76, v76 quad_perm:[2,3,0,1] row_mask:0xf bank_mask:0xf
	v_add_f32_dpp v80, v80, v80 quad_perm:[2,3,0,1] row_mask:0xf bank_mask:0xf
	v_add_f32_dpp v84, v84, v84 quad_perm:[2,3,0,1] row_mask:0xf bank_mask:0xf
	v_add_f32_dpp v88, v88, v88 quad_perm:[2,3,0,1] row_mask:0xf bank_mask:0xf
	v_add_f32_dpp v92, v92, v92 quad_perm:[2,3,0,1] row_mask:0xf bank_mask:0xf
	v_add_f32_dpp v96, v96, v96 quad_perm:[2,3,0,1] row_mask:0xf bank_mask:0xf
	s_nop 1
	v_add_f32_dpp v56, v56, v56 row_half_mirror row_mask:0xf bank_mask:0xf
	v_add_f32_dpp v60, v60, v60 row_half_mirror row_mask:0xf bank_mask:0xf
	v_add_f32_dpp v64, v64, v64 row_half_mirror row_mask:0xf bank_mask:0xf
	v_add_f32_dpp v68, v68, v68 row_half_mirror row_mask:0xf bank_mask:0xf
	v_add_f32_dpp v72, v72, v72 row_half_mirror row_mask:0xf bank_mask:0xf
	v_add_f32_dpp v76, v76, v76 row_half_mirror row_mask:0xf bank_mask:0xf
	v_add_f32_dpp v80, v80, v80 row_half_mirror row_mask:0xf bank_mask:0xf
	v_add_f32_dpp v84, v84, v84 row_half_mirror row_mask:0xf bank_mask:0xf
	v_add_f32_dpp v88, v88, v88 row_half_mirror row_mask:0xf bank_mask:0xf
	v_add_f32_dpp v92, v92, v92 row_half_mirror row_mask:0xf bank_mask:0xf
	v_add_f32_dpp v96, v96, v96 row_half_mirror row_mask:0xf bank_mask:0xf
	s_nop 1
	v_add_f32_dpp v56, v56, v56 row_mirror row_mask:0xf bank_mask:0xf
	v_add_f32_dpp v60, v60, v60 row_mirror row_mask:0xf bank_mask:0xf
	v_add_f32_dpp v64, v64, v64 row_mirror row_mask:0xf bank_mask:0xf
	v_add_f32_dpp v68, v68, v68 row_mirror row_mask:0xf bank_mask:0xf
	v_add_f32_dpp v72, v72, v72 row_mirror row_mask:0xf bank_mask:0xf
	v_add_f32_dpp v76, v76, v76 row_mirror row_mask:0xf bank_mask:0xf
	v_add_f32_dpp v80, v80, v80 row_mirror row_mask:0xf bank_mask:0xf
	v_add_f32_dpp v84, v84, v84 row_mirror row_mask:0xf bank_mask:0xf
	v_add_f32_dpp v88, v88, v88 row_mirror row_mask:0xf bank_mask:0xf
	v_add_f32_dpp v92, v92, v92 row_mirror row_mask:0xf bank_mask:0xf
	v_add_f32_dpp v96, v96, v96 row_mirror row_mask:0xf bank_mask:0xf
	s_nop 1
	s_mov_b32 s82, 0x10001
	s_mov_b32 s83, 0x10001
	s_mov_b64 exec, s[82:83]
	ds_write_b32 v48, v56 offset:1712
	v_max_f32_e32 v40, v40, v56
	ds_write_b32 v48, v60 offset:1728
	v_max_f32_e32 v40, v40, v60
	ds_write_b32 v48, v64 offset:1744
	v_max_f32_e32 v40, v40, v64
	ds_write_b32 v48, v68 offset:1760
	v_max_f32_e32 v40, v40, v68
	ds_write_b32 v48, v72 offset:1776
	v_max_f32_e32 v40, v40, v72
	ds_write_b32 v48, v76 offset:1792
	v_max_f32_e32 v40, v40, v76
	ds_write_b32 v48, v80 offset:1808
	v_max_f32_e32 v40, v40, v80
	ds_write_b32 v48, v84 offset:1824
	v_max_f32_e32 v40, v40, v84
	ds_write_b32 v48, v88 offset:1840
	v_max_f32_e32 v40, v40, v88
	ds_write_b32 v48, v92 offset:1856
	v_max_f32_e32 v40, v40, v92
	ds_write_b32 v48, v96 offset:1872
	v_max_f32_e32 v40, v40, v96
	s_mov_b64 exec, -1
	s_nop 4
	s_waitcnt vmcnt(0)
; #define LAS __attribute__((address_space(3)))
; DI float bflo(unsigned w) { return __uint_as_float(w << 16); }
; DI float bfhi(unsigned w) { return __uint_as_float(w & 0xffff0000u); }
; DI void attn_sample_unit(const Params& p, int u, const bf16_t* Q, const bf16_t* Kb, const bf16_t* Vb, bf16_t* att, LAS float* sl, int lane) {
;     ...
;     for (int e = 0; e < 9; ++e) { const int pat = e / 3, r = e - 3 * pat; const int dil = 1 << (2 * pat);
;         const int j = lane + 64 * r; const bool valid = j <= 128; const int idx = 2048 + t - dil * (valid ? j : 0);
;         float dot = 0.f;
;         if (idx >= 2048) { const bf16_t* kp = Kb + ((size_t)NP + b * 4 + (idx - 2048)) * 1024 + h * 64;
; #pragma unroll
;             for (int d8 = 0; d8 < 8; ++d8) { const u32x4 kw = *(const u32x4*)(kp + 8 * d8); const f32x4 q0 = *(const LAS f32x4*)(sl + 8 * d8), q1 = *(const LAS f32x4*)(sl + 8 * d8 + 4);
;                 dot += (bflo(kw.x) * q0[0] + bfhi(kw.x) * q0[1]) + (bflo(kw.y) * q0[2] + bfhi(kw.y) * q0[3]) + (bflo(kw.z) * q1[0] + bfhi(kw.z) * q1[1]) + (bflo(kw.w) * q1[2] + bfhi(kw.w) * q1[3]); } }
;         else { const float* kp = ck + (((size_t)b * 2048 + idx) * 16 + h) * 64;
; #pragma unroll
;             for (int d4 = 0; d4 < 16; ++d4) { const f32x4 kv = *(const f32x4*)(kp + 4 * d4); const f32x4 qv = *(const LAS f32x4*)(sl + 4 * d4); dot += (kv[0] * qv[0] + kv[1] * qv[1]) + (kv[2] * qv[2] + kv[3] * qv[3]); } }
;         if (valid) { sl[64 + pat * 192 + j] = dot; mx = fmaxf(mx, dot); } }
;     mx = wave_max(mx);
	v_mul_f32_e32 v110, v110, v44
	v_mul_f32_e32 v114, v114, v44
	v_mul_f32_e32 v118, v118, v44
	v_mul_f32_e32 v122, v122, v44
	v_mul_f32_e32 v214, v214, v44
	v_mul_f32_e32 v218, v218, v44
	v_mul_f32_e32 v222, v222, v44
	v_mul_f32_e32 v226, v226, v44
	v_mul_f32_e32 v230, v230, v44
	v_mul_f32_e32 v234, v234, v44
	v_mul_f32_e32 v238, v238, v44
	v_fmac_f32_e32 v110, v111, v45
	v_fmac_f32_e32 v114, v115, v45
	v_fmac_f32_e32 v118, v119, v45
	v_fmac_f32_e32 v122, v123, v45
	v_fmac_f32_e32 v214, v215, v45
	v_fmac_f32_e32 v218, v219, v45
	v_fmac_f32_e32 v222, v223, v45
	v_fmac_f32_e32 v226, v227, v45
	v_fmac_f32_e32 v230, v231, v45
	v_fmac_f32_e32 v234, v235, v45
	v_fmac_f32_e32 v238, v239, v45
	v_fmac_f32_e32 v110, v112, v46
	v_fmac_f32_e32 v114, v116, v46
	v_fmac_f32_e32 v118, v120, v46
	v_fmac_f32_e32 v122, v124, v46
	v_fmac_f32_e32 v214, v216, v46
	v_fmac_f32_e32 v218, v220, v46
	v_fmac_f32_e32 v222, v224, v46
	v_fmac_f32_e32 v226, v228, v46
	v_fmac_f32_e32 v230, v232, v46
	v_fmac_f32_e32 v234, v236, v46
	v_fmac_f32_e32 v238, v240, v46
	v_fmac_f32_e32 v110, v113, v47
	v_fmac_f32_e32 v114, v117, v47
	v_fmac_f32_e32 v118, v121, v47
	v_fmac_f32_e32 v122, v125, v47
	v_fmac_f32_e32 v214, v217, v47
	v_fmac_f32_e32 v218, v221, v47
	v_fmac_f32_e32 v222, v225, v47
	v_fmac_f32_e32 v226, v229, v47
	v_fmac_f32_e32 v230, v233, v47
	v_fmac_f32_e32 v234, v237, v47
	v_fmac_f32_e32 v238, v241, v47
	s_nop 1
	v_add_f32_dpp v110, v110, v110 quad_perm:[1,0,3,2] row_mask:0xf bank_mask:0xf
	v_add_f32_dpp v114, v114, v114 quad_perm:[1,0,3,2] row_mask:0xf bank_mask:0xf
	v_add_f32_dpp v118, v118, v118 quad_perm:[1,0,3,2] row_mask:0xf bank_mask:0xf
	v_add_f32_dpp v122, v122, v122 quad_perm:[1,0,3,2] row_mask:0xf bank_mask:0xf
	v_add_f32_dpp v214, v214, v214 quad_perm:[1,0,3,2] row_mask:0xf bank_mask:0xf
	v_add_f32_dpp v218, v218, v218 quad_perm:[1,0,3,2] row_mask:0xf bank_mask:0xf
	v_add_f32_dpp v222, v222, v222 quad_perm:[1,0,3,2] row_mask:0xf bank_mask:0xf
	v_add_f32_dpp v226, v226, v226 quad_perm:[1,0,3,2] row_mask:0xf bank_mask:0xf
	v_add_f32_dpp v230, v230, v230 quad_perm:[1,0,3,2] row_mask:0xf bank_mask:0xf
	v_add_f32_dpp v234, v234, v234 quad_perm:[1,0,3,2] row_mask:0xf bank_mask:0xf
	v_add_f32_dpp v238, v238, v238 quad_perm:[1,0,3,2] row_mask:0xf bank_mask:0xf
	s_nop 1
	v_add_f32_dpp v110, v110, v110 quad_perm:[2,3,0,1] row_mask:0xf bank_mask:0xf
	v_add_f32_dpp v114, v114, v114 quad_perm:[2,3,0,1] row_mask:0xf bank_mask:0xf
	v_add_f32_dpp v118, v118, v118 quad_perm:[2,3,0,1] row_mask:0xf bank_mask:0xf
	v_add_f32_dpp v122, v122, v122 quad_perm:[2,3,0,1] row_mask:0xf bank_mask:0xf
	v_add_f32_dpp v214, v214, v214 quad_perm:[2,3,0,1] row_mask:0xf bank_mask:0xf
	v_add_f32_dpp v218, v218, v218 quad_perm:[2,3,0,1] row_mask:0xf bank_mask:0xf
	v_add_f32_dpp v222, v222, v222 quad_perm:[2,3,0,1] row_mask:0xf bank_mask:0xf
	v_add_f32_dpp v226, v226, v226 quad_perm:[2,3,0,1] row_mask:0xf bank_mask:0xf
	v_add_f32_dpp v230, v230, v230 quad_perm:[2,3,0,1] row_mask:0xf bank_mask:0xf
	v_add_f32_dpp v234, v234, v234 quad_perm:[2,3,0,1] row_mask:0xf bank_mask:0xf
	v_add_f32_dpp v238, v238, v238 quad_perm:[2,3,0,1] row_mask:0xf bank_mask:0xf
	s_nop 1
	v_add_f32_dpp v110, v110, v110 row_half_mirror row_mask:0xf bank_mask:0xf
	v_add_f32_dpp v114, v114, v114 row_half_mirror row_mask:0xf bank_mask:0xf
	v_add_f32_dpp v118, v118, v118 row_half_mirror row_mask:0xf bank_mask:0xf
	v_add_f32_dpp v122, v122, v122 row_half_mirror row_mask:0xf bank_mask:0xf
	v_add_f32_dpp v214, v214, v214 row_half_mirror row_mask:0xf bank_mask:0xf
	v_add_f32_dpp v218, v218, v218 row_half_mirror row_mask:0xf bank_mask:0xf
	v_add_f32_dpp v222, v222, v222 row_half_mirror row_mask:0xf bank_mask:0xf
	v_add_f32_dpp v226, v226, v226 row_half_mirror row_mask:0xf bank_mask:0xf
	v_add_f32_dpp v230, v230, v230 row_half_mirror row_mask:0xf bank_mask:0xf
	v_add_f32_dpp v234, v234, v234 row_half_mirror row_mask:0xf bank_mask:0xf
	v_add_f32_dpp v238, v238, v238 row_half_mirror row_mask:0xf bank_mask:0xf
	s_nop 1
	v_add_f32_dpp v110, v110, v110 row_mirror row_mask:0xf bank_mask:0xf
	v_add_f32_dpp v114, v114, v114 row_mirror row_mask:0xf bank_mask:0xf
	v_add_f32_dpp v118, v118, v118 row_mirror row_mask:0xf bank_mask:0xf
	v_add_f32_dpp v122, v122, v122 row_mirror row_mask:0xf bank_mask:0xf
	v_add_f32_dpp v214, v214, v214 row_mirror row_mask:0xf bank_mask:0xf
	v_add_f32_dpp v218, v218, v218 row_mirror row_mask:0xf bank_mask:0xf
	v_add_f32_dpp v222, v222, v222 row_mirror row_mask:0xf bank_mask:0xf
	v_add_f32_dpp v226, v226, v226 row_mirror row_mask:0xf bank_mask:0xf
	v_add_f32_dpp v230, v230, v230 row_mirror row_mask:0xf bank_mask:0xf
	v_add_f32_dpp v234, v234, v234 row_mirror row_mask:0xf bank_mask:0xf
	v_add_f32_dpp v238, v238, v238 row_mirror row_mask:0xf bank_mask:0xf
	s_nop 1
	s_mov_b32 s82, 0x10001
	s_mov_b32 s83, 0x10001
	s_mov_b64 exec, s[82:83]
	ds_write_b32 v48, v110 offset:1888
	v_max_f32_e32 v40, v40, v110
	ds_write_b32 v48, v114 offset:1904
	v_max_f32_e32 v40, v40, v114
	ds_write_b32 v48, v118 offset:1920
	v_max_f32_e32 v40, v40, v118
	ds_write_b32 v48, v122 offset:1936
	v_max_f32_e32 v40, v40, v122
	ds_write_b32 v48, v214 offset:1952
	v_max_f32_e32 v40, v40, v214
	ds_write_b32 v48, v218 offset:1968
	v_max_f32_e32 v40, v40, v218
	ds_write_b32 v48, v222 offset:1984
	v_max_f32_e32 v40, v40, v222
	ds_write_b32 v48, v226 offset:2000
	v_max_f32_e32 v40, v40, v226
	ds_write_b32 v48, v230 offset:2016
	v_max_f32_e32 v40, v40, v230
	ds_write_b32 v48, v234 offset:2032
	v_max_f32_e32 v40, v40, v234
	s_mov_b64 exec, 1
	ds_write_b32 v48, v238 offset:2048
	v_max_f32_e32 v40, v40, v238
	s_mov_b64 exec, -1
	s_nop 4
	s_waitcnt vmcnt(0) lgkmcnt(0)
